# baseline (speedup 1.0000x reference)
; #define PG8_STAGE(bufoff, gbase, voff) do { _Pragma("unroll") for (int _i = 0; _i < 2; ++_i) \
;         __builtin_amdgcn_global_load_lds((const unsigned*)((const char*)(gbase) + (voff)[_i]), (LAS unsigned*)(lds + (bufoff) + ldsw + _i * 8192), 16, 0, 0); } while (0)
; #define PG8_LDA(dst, b, h) do { _Pragma("unroll") for (int m = 0; m < 4; ++m) _Pragma("unroll") for (int k = 0; k < 2; ++k) dst[m][k] = *(const LAS bf16x8*)(lds + PG8_SA(b, h) + aoff + m * 2048 + k * 1024); } while (0)
; #define PG8_LDB(dst, b, h) do { _Pragma("unroll") for (int n = 0; n < 2; ++n) _Pragma("unroll") for (int k = 0; k < 2; ++k) dst[n][k] = *(const LAS bf16x8*)(lds + PG8_SB(b, h) + boff + n * 2048 + k * 1024); } while (0)
; #define PG8_BAR __builtin_amdgcn_s_barrier()
; template <class Epi, class Pre, bool AG = false>
; __device__ __forceinline__ void gemm_phase(LAS unsigned char* lds, const Gemm g, const StaticOrder& S, const Epi& E, const Pre& P) {
;     ...
;         const bool has_next = S.next(ui + 1, nxt);
;         const char* nA = has_next ? (const char*)g.A + (size_t)nxt.pm * tstepA : cA; const char* nB = has_next ? (const char*)g.Bt + (size_t)nxt.pn * tstep : cB;
;         for (int t = 0; t < nt; t += 2) {
;             const bool last = (t == nt - 2);
;             const char* a1 = cA + (size_t)(t + 1) * kstepA;
;             const char* a2 = last ? nA : cA + (size_t)(t + 2) * kstepA; const char* b2 = last ? nB : cB + (size_t)(t + 2) * kstep;
;             const char* a3 = a2 + kstepA; const char* b3 = b2 + kstep;
;             if constexpr (Epi::MIDK) { if (t == E.midk_t) E.mid(acc, cur, ui, wr, wc, fr, fq); }
;             PG8_LDB(B0, 0, 0); PG8_LDB(B1, 0, 1); PG8_SCHED; PG8_LDA(At, 0, 0); PG8_STAGE(PG8_SA(1, 1), a1 + hstepA, voffA);
;             PG8_WAIT_V(8); PG8_WAIT_L(0); PG8_BAR; PG8_MMA(0, 0, At, B0); PG8_MMA(0, 1, At, B1); PG8_BAR; PG8_SCHED;
;             PG8_LDA(At, 0, 1); PG8_STAGE(PG8_SB(0, 0), b2, voffB); PG8_STAGE(PG8_SB(0, 1), b2 + hstep, voffB); PG8_STAGE(PG8_SA(0, 0), a2, voffA);
;             PG8_WAIT_V(8); PG8_WAIT_L(0); PG8_BAR; PG8_MMA(1, 0, At, B0); PG8_MMA(1, 1, At, B1); PG8_BAR; PG8_SCHED;
;             PG8_LDB(B0, 1, 0); PG8_LDB(B1, 1, 1); PG8_SCHED; PG8_LDA(At, 1, 0); PG8_STAGE(PG8_SA(0, 1), a2 + hstepA, voffA);
;             PG8_WAIT_V(8); PG8_WAIT_L(0); PG8_BAR; PG8_MMA(0, 0, At, B0); PG8_MMA(0, 1, At, B1); PG8_BAR; PG8_SCHED;
.LBB0_379:
	s_add_u32 s79, s56, 0x100
	s_addc_u32 s84, s57, 0
	s_mov_b32 s85, -2
	s_waitcnt lgkmcnt(0)
	s_add_u32 s10, s54, 0x100
	s_addc_u32 s11, s55, 0
	s_add_i32 s86, 0, 0x10000
	s_cmp_eq_u32 s85, 40
	s_cselect_b32 s59, s45, s11
	s_cselect_b32 s58, s44, s10
	s_cselect_b32 s57, s47, s84
	s_cselect_b32 s56, s46, s79
	s_add_i32 s87, 0, 0x14000
	v_add_u32_e32 v134, s86, v198
	v_add_u32_e32 v168, s87, v198
	ds_read_b128 v[114:117], v134
	ds_read_b128 v[118:121], v134 offset:1024
	ds_read_b128 v[122:125], v134 offset:2048
	ds_read_b128 v[134:137], v134 offset:3072
	ds_read_b128 v[146:149], v168
	ds_read_b128 v[150:153], v168 offset:1024
	ds_read_b128 v[164:167], v168 offset:2048
	ds_read_b128 v[168:171], v168 offset:3072
	v_lshl_add_u64 v[176:177], s[54:55], 0, v[160:161]
	s_add_i32 m0, s30, 0xc000
	ds_read_b128 v[172:175], v199
	ds_read_b128 v[194:197], v199 offset:1024
	ds_read_b128 v[200:203], v199 offset:2048
	ds_read_b128 v[204:207], v199 offset:3072
	ds_read_b128 v[208:211], v199 offset:4096
	ds_read_b128 v[212:215], v199 offset:5120
	ds_read_b128 v[216:219], v199 offset:6144
	ds_read_b128 v[220:223], v199 offset:7168
	global_load_lds_dwordx4 v[176:177], off
	v_lshl_add_u64 v[176:177], s[54:55], 0, v[162:163]
	s_add_i32 m0, s30, 0xe000
	s_nop 0
	global_load_lds_dwordx4 v[176:177], off
	s_waitcnt vmcnt(8)
	s_waitcnt lgkmcnt(0)
	s_barrier
	s_setprio 1
	s_waitcnt lgkmcnt(0)
	v_mfma_f32_16x16x32_bf16 v[142:145], v[114:117], v[172:175], 0
	v_mfma_f32_16x16x32_bf16 v[138:141], v[122:125], v[172:175], 0
	v_mfma_f32_16x16x32_bf16 v[110:113], v[114:117], v[200:203], 0
	v_mfma_f32_16x16x32_bf16 v[106:109], v[122:125], v[200:203], 0
	v_mfma_f32_16x16x32_bf16 v[94:97], v[114:117], v[208:211], 0
	v_mfma_f32_16x16x32_bf16 v[90:93], v[122:125], v[208:211], 0
	v_mfma_f32_16x16x32_bf16 v[78:81], v[114:117], v[216:219], 0
	v_mfma_f32_16x16x32_bf16 v[74:77], v[122:125], v[216:219], 0
	v_mfma_f32_16x16x32_bf16 v[142:145], v[118:121], v[194:197], v[142:145]
	v_mfma_f32_16x16x32_bf16 v[138:141], v[134:137], v[194:197], v[138:141]
	v_mfma_f32_16x16x32_bf16 v[110:113], v[118:121], v[204:207], v[110:113]
	v_mfma_f32_16x16x32_bf16 v[106:109], v[134:137], v[204:207], v[106:109]
	v_mfma_f32_16x16x32_bf16 v[94:97], v[118:121], v[212:215], v[94:97]
	v_mfma_f32_16x16x32_bf16 v[90:93], v[134:137], v[212:215], v[90:93]
	v_mfma_f32_16x16x32_bf16 v[78:81], v[118:121], v[220:223], v[78:81]
	v_mfma_f32_16x16x32_bf16 v[74:77], v[134:137], v[220:223], v[74:77]
	s_setprio 0
	s_setprio 1
	v_mfma_f32_16x16x32_bf16 v[130:133], v[146:149], v[172:175], 0
	v_mfma_f32_16x16x32_bf16 v[126:129], v[164:167], v[172:175], 0
	v_mfma_f32_16x16x32_bf16 v[102:105], v[146:149], v[200:203], 0
	v_mfma_f32_16x16x32_bf16 v[98:101], v[164:167], v[200:203], 0
	v_mfma_f32_16x16x32_bf16 v[86:89], v[146:149], v[208:211], 0
	v_mfma_f32_16x16x32_bf16 v[82:85], v[164:167], v[208:211], 0
	v_mfma_f32_16x16x32_bf16 v[70:73], v[146:149], v[216:219], 0
	v_mfma_f32_16x16x32_bf16 v[66:69], v[164:167], v[216:219], 0
	v_mfma_f32_16x16x32_bf16 v[130:133], v[150:153], v[194:197], v[130:133]
	v_mfma_f32_16x16x32_bf16 v[126:129], v[168:171], v[194:197], v[126:129]
	v_mfma_f32_16x16x32_bf16 v[102:105], v[150:153], v[204:207], v[102:105]
	v_mfma_f32_16x16x32_bf16 v[98:101], v[168:171], v[204:207], v[98:101]
	v_mfma_f32_16x16x32_bf16 v[86:89], v[150:153], v[212:215], v[86:89]
	v_mfma_f32_16x16x32_bf16 v[82:85], v[168:171], v[212:215], v[82:85]
	v_mfma_f32_16x16x32_bf16 v[70:73], v[150:153], v[220:223], v[70:73]
	v_mfma_f32_16x16x32_bf16 v[66:69], v[168:171], v[220:223], v[66:69]
	s_setprio 0
	s_barrier
	s_add_i32 s54, s86, s25
	v_lshl_add_u64 v[176:177], s[56:57], 0, v[0:1]
	s_mov_b32 m0, s54
	ds_read_b128 v[172:175], v199 offset:16384
	ds_read_b128 v[194:197], v199 offset:17408
	ds_read_b128 v[200:203], v199 offset:18432
	ds_read_b128 v[204:207], v199 offset:19456
	ds_read_b128 v[208:211], v199 offset:20480
	ds_read_b128 v[212:215], v199 offset:21504
	ds_read_b128 v[216:219], v199 offset:22528
	ds_read_b128 v[220:223], v199 offset:23552
	global_load_lds_dwordx4 v[176:177], off
	s_add_i32 m0, s54, 0x2000
	s_add_u32 s54, s56, 0xb0000
	v_lshl_add_u64 v[178:179], s[56:57], 0, v[154:155]
	s_addc_u32 s55, s57, 0
	s_add_i32 s86, s87, s25
	global_load_lds_dwordx4 v[178:179], off
	v_lshl_add_u64 v[180:181], s[54:55], 0, v[0:1]
	s_mov_b32 m0, s86
	v_lshl_add_u64 v[182:183], s[58:59], 0, v[156:157]
	global_load_lds_dwordx4 v[180:181], off
	v_lshl_add_u64 v[180:181], s[54:55], 0, v[154:155]
	s_add_i32 m0, s86, 0x2000
	s_nop 0
	global_load_lds_dwordx4 v[180:181], off
	v_lshl_add_u64 v[180:181], s[58:59], 0, v[158:159]
	s_mov_b32 m0, s30
	s_nop 0
	global_load_lds_dwordx4 v[180:181], off
	s_mov_b32 m0, s31
	s_nop 0
	global_load_lds_dwordx4 v[182:183], off
	s_waitcnt vmcnt(8)
	s_waitcnt lgkmcnt(0)
	s_barrier
; #define PG8_STAGE(bufoff, gbase, voff) do { _Pragma("unroll") for (int _i = 0; _i < 2; ++_i) \
;         __builtin_amdgcn_global_load_lds((const unsigned*)((const char*)(gbase) + (voff)[_i]), (LAS unsigned*)(lds + (bufoff) + ldsw + _i * 8192), 16, 0, 0); } while (0)
; #define PG8_LDA(dst, b, h) do { _Pragma("unroll") for (int m = 0; m < 4; ++m) _Pragma("unroll") for (int k = 0; k < 2; ++k) dst[m][k] = *(const LAS bf16x8*)(lds + PG8_SA(b, h) + aoff + m * 2048 + k * 1024); } while (0)
; #define PG8_LDB(dst, b, h) do { _Pragma("unroll") for (int n = 0; n < 2; ++n) _Pragma("unroll") for (int k = 0; k < 2; ++k) dst[n][k] = *(const LAS bf16x8*)(lds + PG8_SB(b, h) + boff + n * 2048 + k * 1024); } while (0)
; #define PG8_MMA(ai, bj, At, Bt) do { __builtin_amdgcn_s_setprio(1); _Pragma("unroll") for (int m = 0; m < 4; ++m) _Pragma("unroll") for (int n = 0; n < 2; ++n) _Pragma("unroll") for (int k = 0; k < 2; ++k) \
;         acc[ai][bj][m][n] = __builtin_amdgcn_mfma_f32_16x16x32_bf16(Bt[n][k], At[m][k], acc[ai][bj][m][n], 0, 0, 0); __builtin_amdgcn_s_setprio(0); } while (0)
; #define PG8_WAIT_V(n) asm volatile("s_waitcnt vmcnt(" #n ")" ::: "memory")
; template <class Epi, class Pre, bool AG = false>
; __device__ __forceinline__ void gemm_phase(LAS unsigned char* lds, const Gemm g, const StaticOrder& S, const Epi& E, const Pre& P) {
;     ...
;             PG8_LDB(B0, 0, 0); PG8_LDB(B1, 0, 1); PG8_SCHED; PG8_LDA(At, 0, 0); PG8_STAGE(PG8_SA(1, 1), a1 + hstepA, voffA);
;             PG8_WAIT_V(8); PG8_WAIT_L(0); PG8_BAR; PG8_MMA(0, 0, At, B0); PG8_MMA(0, 1, At, B1); PG8_BAR; PG8_SCHED;
;             PG8_LDA(At, 0, 1); PG8_STAGE(PG8_SB(0, 0), b2, voffB); PG8_STAGE(PG8_SB(0, 1), b2 + hstep, voffB); PG8_STAGE(PG8_SA(0, 0), a2, voffA);
;             PG8_WAIT_V(8); PG8_WAIT_L(0); PG8_BAR; PG8_MMA(1, 0, At, B0); PG8_MMA(1, 1, At, B1); PG8_BAR; PG8_SCHED;
;             PG8_LDB(B0, 1, 0); PG8_LDB(B1, 1, 1); PG8_SCHED; PG8_LDA(At, 1, 0); PG8_STAGE(PG8_SA(0, 1), a2 + hstepA, voffA);
;             PG8_WAIT_V(8); PG8_WAIT_L(0); PG8_BAR; PG8_MMA(0, 0, At, B0); PG8_MMA(0, 1, At, B1); PG8_BAR; PG8_SCHED;
;             PG8_LDA(At, 1, 1); PG8_STAGE(PG8_SB(1, 0), b3, voffB); PG8_STAGE(PG8_SB(1, 1), b3 + hstep, voffB); PG8_STAGE(PG8_SA(1, 0), a3, voffA);
;             PG8_WAIT_V(8); PG8_WAIT_L(0); PG8_BAR; PG8_MMA(1, 0, At, B0); PG8_MMA(1, 1, At, B1); PG8_BAR; PG8_SCHED;
	s_setprio 1
	s_waitcnt lgkmcnt(0)
	v_mfma_f32_16x16x32_bf16 v[62:65], v[114:117], v[172:175], 0
	v_mfma_f32_16x16x32_bf16 v[58:61], v[122:125], v[172:175], 0
	v_mfma_f32_16x16x32_bf16 v[46:49], v[114:117], v[200:203], 0
	v_mfma_f32_16x16x32_bf16 v[42:45], v[122:125], v[200:203], 0
	v_mfma_f32_16x16x32_bf16 v[30:33], v[114:117], v[208:211], 0
	v_mfma_f32_16x16x32_bf16 v[26:29], v[122:125], v[208:211], 0
	v_mfma_f32_16x16x32_bf16 v[14:17], v[114:117], v[216:219], 0
	v_mfma_f32_16x16x32_bf16 v[10:13], v[122:125], v[216:219], 0
	v_mfma_f32_16x16x32_bf16 v[62:65], v[118:121], v[194:197], v[62:65]
	v_mfma_f32_16x16x32_bf16 v[58:61], v[134:137], v[194:197], v[58:61]
	v_mfma_f32_16x16x32_bf16 v[46:49], v[118:121], v[204:207], v[46:49]
	v_mfma_f32_16x16x32_bf16 v[42:45], v[134:137], v[204:207], v[42:45]
	v_mfma_f32_16x16x32_bf16 v[30:33], v[118:121], v[212:215], v[30:33]
	v_mfma_f32_16x16x32_bf16 v[26:29], v[134:137], v[212:215], v[26:29]
	v_mfma_f32_16x16x32_bf16 v[14:17], v[118:121], v[220:223], v[14:17]
	v_mfma_f32_16x16x32_bf16 v[10:13], v[134:137], v[220:223], v[10:13]
	s_setprio 0
	s_setprio 1
	v_mfma_f32_16x16x32_bf16 v[54:57], v[146:149], v[172:175], 0
	v_mfma_f32_16x16x32_bf16 v[50:53], v[164:167], v[172:175], 0
	v_mfma_f32_16x16x32_bf16 v[38:41], v[146:149], v[200:203], 0
	v_mfma_f32_16x16x32_bf16 v[34:37], v[164:167], v[200:203], 0
	v_mfma_f32_16x16x32_bf16 v[22:25], v[146:149], v[208:211], 0
	v_mfma_f32_16x16x32_bf16 v[18:21], v[164:167], v[208:211], 0
	v_mfma_f32_16x16x32_bf16 v[6:9], v[146:149], v[216:219], 0
	v_mfma_f32_16x16x32_bf16 v[2:5], v[164:167], v[216:219], 0
	v_mfma_f32_16x16x32_bf16 v[54:57], v[150:153], v[194:197], v[54:57]
	v_mfma_f32_16x16x32_bf16 v[50:53], v[168:171], v[194:197], v[50:53]
	v_mfma_f32_16x16x32_bf16 v[38:41], v[150:153], v[204:207], v[38:41]
	v_mfma_f32_16x16x32_bf16 v[34:37], v[168:171], v[204:207], v[34:37]
	v_mfma_f32_16x16x32_bf16 v[22:25], v[150:153], v[212:215], v[22:25]
	v_mfma_f32_16x16x32_bf16 v[18:21], v[168:171], v[212:215], v[18:21]
	v_mfma_f32_16x16x32_bf16 v[6:9], v[150:153], v[220:223], v[6:9]
	v_mfma_f32_16x16x32_bf16 v[2:5], v[168:171], v[220:223], v[2:5]
	s_setprio 0
	s_barrier
	s_add_i32 s86, 0, 0x18000
	s_add_i32 s87, 0, 0x1c000
	v_add_u32_e32 v134, s86, v198
	v_add_u32_e32 v168, s87, v198
	ds_read_b128 v[114:117], v134
	ds_read_b128 v[118:121], v134 offset:1024
	ds_read_b128 v[122:125], v134 offset:2048
	ds_read_b128 v[134:137], v134 offset:3072
	ds_read_b128 v[146:149], v168
	ds_read_b128 v[150:153], v168 offset:1024
	ds_read_b128 v[164:167], v168 offset:2048
	ds_read_b128 v[168:171], v168 offset:3072
	s_add_u32 s54, s58, 0xb0000
	s_addc_u32 s55, s59, 0
	s_mov_b32 m0, s38
	v_lshl_add_u64 v[188:189], s[54:55], 0, v[158:159]
	ds_read_b128 v[172:175], v199 offset:32768
	ds_read_b128 v[194:197], v199 offset:33792
	ds_read_b128 v[200:203], v199 offset:34816
	ds_read_b128 v[204:207], v199 offset:35840
	ds_read_b128 v[208:211], v199 offset:36864
	ds_read_b128 v[212:215], v199 offset:37888
	ds_read_b128 v[216:219], v199 offset:38912
	ds_read_b128 v[220:223], v199 offset:39936
	global_load_lds_dwordx4 v[188:189], off
	v_lshl_add_u64 v[188:189], s[54:55], 0, v[156:157]
	s_mov_b32 m0, s48
	s_nop 0
	global_load_lds_dwordx4 v[188:189], off
	s_waitcnt vmcnt(8)
	s_waitcnt lgkmcnt(0)
	s_barrier
	s_setprio 1
	s_waitcnt lgkmcnt(0)
	v_mfma_f32_16x16x32_bf16 v[142:145], v[114:117], v[172:175], v[142:145]
	v_mfma_f32_16x16x32_bf16 v[138:141], v[122:125], v[172:175], v[138:141]
	v_mfma_f32_16x16x32_bf16 v[110:113], v[114:117], v[200:203], v[110:113]
	v_mfma_f32_16x16x32_bf16 v[106:109], v[122:125], v[200:203], v[106:109]
	v_mfma_f32_16x16x32_bf16 v[94:97], v[114:117], v[208:211], v[94:97]
	v_mfma_f32_16x16x32_bf16 v[90:93], v[122:125], v[208:211], v[90:93]
	v_mfma_f32_16x16x32_bf16 v[78:81], v[114:117], v[216:219], v[78:81]
	v_mfma_f32_16x16x32_bf16 v[74:77], v[122:125], v[216:219], v[74:77]
	v_mfma_f32_16x16x32_bf16 v[142:145], v[118:121], v[194:197], v[142:145]
	v_mfma_f32_16x16x32_bf16 v[138:141], v[134:137], v[194:197], v[138:141]
	v_mfma_f32_16x16x32_bf16 v[110:113], v[118:121], v[204:207], v[110:113]
	v_mfma_f32_16x16x32_bf16 v[106:109], v[134:137], v[204:207], v[106:109]
	v_mfma_f32_16x16x32_bf16 v[94:97], v[118:121], v[212:215], v[94:97]
	v_mfma_f32_16x16x32_bf16 v[90:93], v[134:137], v[212:215], v[90:93]
	v_mfma_f32_16x16x32_bf16 v[78:81], v[118:121], v[220:223], v[78:81]
	v_mfma_f32_16x16x32_bf16 v[74:77], v[134:137], v[220:223], v[74:77]
	s_setprio 0
	s_setprio 1
	v_mfma_f32_16x16x32_bf16 v[130:133], v[146:149], v[172:175], v[130:133]
	v_mfma_f32_16x16x32_bf16 v[126:129], v[164:167], v[172:175], v[126:129]
	v_mfma_f32_16x16x32_bf16 v[102:105], v[146:149], v[200:203], v[102:105]
	v_mfma_f32_16x16x32_bf16 v[98:101], v[164:167], v[200:203], v[98:101]
	v_mfma_f32_16x16x32_bf16 v[86:89], v[146:149], v[208:211], v[86:89]
	v_mfma_f32_16x16x32_bf16 v[82:85], v[164:167], v[208:211], v[82:85]
	v_mfma_f32_16x16x32_bf16 v[70:73], v[146:149], v[216:219], v[70:73]
	v_mfma_f32_16x16x32_bf16 v[66:69], v[164:167], v[216:219], v[66:69]
	v_mfma_f32_16x16x32_bf16 v[130:133], v[150:153], v[194:197], v[130:133]
	v_mfma_f32_16x16x32_bf16 v[126:129], v[168:171], v[194:197], v[126:129]
	v_mfma_f32_16x16x32_bf16 v[102:105], v[150:153], v[204:207], v[102:105]
	v_mfma_f32_16x16x32_bf16 v[98:101], v[168:171], v[204:207], v[98:101]
	v_mfma_f32_16x16x32_bf16 v[86:89], v[150:153], v[212:215], v[86:89]
	v_mfma_f32_16x16x32_bf16 v[82:85], v[168:171], v[212:215], v[82:85]
	v_mfma_f32_16x16x32_bf16 v[70:73], v[150:153], v[220:223], v[70:73]
	v_mfma_f32_16x16x32_bf16 v[66:69], v[168:171], v[220:223], v[66:69]
	s_setprio 0
	s_barrier
; #define PG8_STAGE(bufoff, gbase, voff) do { _Pragma("unroll") for (int _i = 0; _i < 2; ++_i) \
;         __builtin_amdgcn_global_load_lds((const unsigned*)((const char*)(gbase) + (voff)[_i]), (LAS unsigned*)(lds + (bufoff) + ldsw + _i * 8192), 16, 0, 0); } while (0)
; #define PG8_LDA(dst, b, h) do { _Pragma("unroll") for (int m = 0; m < 4; ++m) _Pragma("unroll") for (int k = 0; k < 2; ++k) dst[m][k] = *(const LAS bf16x8*)(lds + PG8_SA(b, h) + aoff + m * 2048 + k * 1024); } while (0)
; #define PG8_LDB(dst, b, h) do { _Pragma("unroll") for (int n = 0; n < 2; ++n) _Pragma("unroll") for (int k = 0; k < 2; ++k) dst[n][k] = *(const LAS bf16x8*)(lds + PG8_SB(b, h) + boff + n * 2048 + k * 1024); } while (0)
; #define PG8_MMA(ai, bj, At, Bt) do { __builtin_amdgcn_s_setprio(1); _Pragma("unroll") for (int m = 0; m < 4; ++m) _Pragma("unroll") for (int n = 0; n < 2; ++n) _Pragma("unroll") for (int k = 0; k < 2; ++k) \
;         acc[ai][bj][m][n] = __builtin_amdgcn_mfma_f32_16x16x32_bf16(Bt[n][k], At[m][k], acc[ai][bj][m][n], 0, 0, 0); __builtin_amdgcn_s_setprio(0); } while (0)
; #define PG8_WAIT_V(n) asm volatile("s_waitcnt vmcnt(" #n ")" ::: "memory")
; #define PG8_WAIT_L(n) asm volatile("s_waitcnt lgkmcnt(" #n ")" ::: "memory")
; #define PG8_BAR __builtin_amdgcn_s_barrier()
; #define PG8_SCHED __builtin_amdgcn_sched_barrier(0)
; template <class Epi, class Pre, bool AG = false>
; __device__ __forceinline__ void gemm_phase(LAS unsigned char* lds, const Gemm g, const StaticOrder& S, const Epi& E, const Pre& P) {
;     ...
;             PG8_LDB(B0, 1, 0); PG8_LDB(B1, 1, 1); PG8_SCHED; PG8_LDA(At, 1, 0); PG8_STAGE(PG8_SA(0, 1), a2 + hstepA, voffA);
;             PG8_WAIT_V(8); PG8_WAIT_L(0); PG8_BAR; PG8_MMA(0, 0, At, B0); PG8_MMA(0, 1, At, B1); PG8_BAR; PG8_SCHED;
;             PG8_LDA(At, 1, 1); PG8_STAGE(PG8_SB(1, 0), b3, voffB); PG8_STAGE(PG8_SB(1, 1), b3 + hstep, voffB); PG8_STAGE(PG8_SA(1, 0), a3, voffA);
;             PG8_WAIT_V(8); PG8_WAIT_L(0); PG8_BAR; PG8_MMA(1, 0, At, B0); PG8_MMA(1, 1, At, B1); PG8_BAR; PG8_SCHED;
;         }
	s_add_i32 s54, s86, s25
	v_lshl_add_u64 v[176:177], v[176:177], 0, s[66:67]
	s_mov_b32 m0, s54
	ds_read_b128 v[172:175], v199 offset:49152
	ds_read_b128 v[194:197], v199 offset:50176
	ds_read_b128 v[200:203], v199 offset:51200
	ds_read_b128 v[204:207], v199 offset:52224
	ds_read_b128 v[208:211], v199 offset:53248
	ds_read_b128 v[212:215], v199 offset:54272
	ds_read_b128 v[216:219], v199 offset:55296
	ds_read_b128 v[220:223], v199 offset:56320
	global_load_lds_dwordx4 v[176:177], off
	s_add_i32 m0, s54, 0x2000
	s_add_u32 s54, s56, 0xb0080
	v_lshl_add_u64 v[176:177], v[178:179], 0, s[66:67]
	s_addc_u32 s55, s57, 0
	s_add_i32 s56, s87, s25
	global_load_lds_dwordx4 v[176:177], off
	v_lshl_add_u64 v[176:177], s[54:55], 0, v[0:1]
	s_mov_b32 m0, s56
	s_nop 0
	global_load_lds_dwordx4 v[176:177], off
	v_lshl_add_u64 v[176:177], s[54:55], 0, v[154:155]
	s_add_i32 m0, s56, 0x2000
	s_nop 0
	global_load_lds_dwordx4 v[176:177], off
	v_lshl_add_u64 v[176:177], v[180:181], 0, s[66:67]
	s_mov_b32 m0, s61
	s_nop 0
	global_load_lds_dwordx4 v[176:177], off
	v_lshl_add_u64 v[176:177], v[182:183], 0, s[66:67]
	s_mov_b32 m0, s70
	s_nop 0
	global_load_lds_dwordx4 v[176:177], off
	s_waitcnt vmcnt(8)
	s_waitcnt lgkmcnt(0)
	s_barrier
	s_setprio 1
	s_waitcnt lgkmcnt(0)
	v_mfma_f32_16x16x32_bf16 v[62:65], v[114:117], v[172:175], v[62:65]
	v_mfma_f32_16x16x32_bf16 v[58:61], v[122:125], v[172:175], v[58:61]
	v_mfma_f32_16x16x32_bf16 v[46:49], v[114:117], v[200:203], v[46:49]
	v_mfma_f32_16x16x32_bf16 v[42:45], v[122:125], v[200:203], v[42:45]
	v_mfma_f32_16x16x32_bf16 v[30:33], v[114:117], v[208:211], v[30:33]
	v_mfma_f32_16x16x32_bf16 v[26:29], v[122:125], v[208:211], v[26:29]
	v_mfma_f32_16x16x32_bf16 v[14:17], v[114:117], v[216:219], v[14:17]
	v_mfma_f32_16x16x32_bf16 v[10:13], v[122:125], v[216:219], v[10:13]
	v_mfma_f32_16x16x32_bf16 v[62:65], v[118:121], v[194:197], v[62:65]
	v_mfma_f32_16x16x32_bf16 v[58:61], v[134:137], v[194:197], v[58:61]
	v_mfma_f32_16x16x32_bf16 v[46:49], v[118:121], v[204:207], v[46:49]
	v_mfma_f32_16x16x32_bf16 v[42:45], v[134:137], v[204:207], v[42:45]
	v_mfma_f32_16x16x32_bf16 v[30:33], v[118:121], v[212:215], v[30:33]
	v_mfma_f32_16x16x32_bf16 v[26:29], v[134:137], v[212:215], v[26:29]
	v_mfma_f32_16x16x32_bf16 v[14:17], v[118:121], v[220:223], v[14:17]
	v_mfma_f32_16x16x32_bf16 v[10:13], v[134:137], v[220:223], v[10:13]
	s_setprio 0
	s_setprio 1
	v_mfma_f32_16x16x32_bf16 v[54:57], v[146:149], v[172:175], v[54:57]
	v_mfma_f32_16x16x32_bf16 v[50:53], v[164:167], v[172:175], v[50:53]
	v_mfma_f32_16x16x32_bf16 v[38:41], v[146:149], v[200:203], v[38:41]
	v_mfma_f32_16x16x32_bf16 v[34:37], v[164:167], v[200:203], v[34:37]
	v_mfma_f32_16x16x32_bf16 v[22:25], v[146:149], v[208:211], v[22:25]
	v_mfma_f32_16x16x32_bf16 v[18:21], v[164:167], v[208:211], v[18:21]
	v_mfma_f32_16x16x32_bf16 v[6:9], v[146:149], v[216:219], v[6:9]
	v_mfma_f32_16x16x32_bf16 v[2:5], v[164:167], v[216:219], v[2:5]
	v_mfma_f32_16x16x32_bf16 v[54:57], v[150:153], v[194:197], v[54:57]
	v_mfma_f32_16x16x32_bf16 v[50:53], v[168:171], v[194:197], v[50:53]
	v_mfma_f32_16x16x32_bf16 v[38:41], v[150:153], v[204:207], v[38:41]
	v_mfma_f32_16x16x32_bf16 v[34:37], v[168:171], v[204:207], v[34:37]
	v_mfma_f32_16x16x32_bf16 v[22:25], v[150:153], v[212:215], v[22:25]
	v_mfma_f32_16x16x32_bf16 v[18:21], v[168:171], v[212:215], v[18:21]
	v_mfma_f32_16x16x32_bf16 v[6:9], v[150:153], v[220:223], v[6:9]
	v_mfma_f32_16x16x32_bf16 v[2:5], v[168:171], v[220:223], v[2:5]
	s_setprio 0
	s_barrier
	s_add_i32 s85, s85, 2
	s_add_u32 s79, s79, 0x100
	s_addc_u32 s84, s84, 0
	s_cmp_gt_u32 s85, 41
	s_mov_b64 s[54:55], s[10:11]
	s_cbranch_scc0 .LBB0_380
	s_branch .Lpeel_d_after

; #define PG8_BAR __builtin_amdgcn_s_barrier()
; template <class Epi, class Pre, bool AG = false>
; __device__ __forceinline__ void gemm_phase(LAS unsigned char* lds, const Gemm g, const StaticOrder& S, const Epi& E, const Pre& P) {
;     ...
;         if (wr == 0) PG8_BAR;
.Lpeel_d_after:
	s_and_b64 vcc, exec, s[42:43]
	s_cbranch_vccz .LBB0_383
	s_barrier

; #define PG8_STAGE(bufoff, gbase, voff) do { _Pragma("unroll") for (int _i = 0; _i < 2; ++_i) \
;         __builtin_amdgcn_global_load_lds((const unsigned*)((const char*)(gbase) + (voff)[_i]), (LAS unsigned*)(lds + (bufoff) + ldsw + _i * 8192), 16, 0, 0); } while (0)
; #define PG8_LDA(dst, b, h) do { _Pragma("unroll") for (int m = 0; m < 4; ++m) _Pragma("unroll") for (int k = 0; k < 2; ++k) dst[m][k] = *(const LAS bf16x8*)(lds + PG8_SA(b, h) + aoff + m * 2048 + k * 1024); } while (0)
; #define PG8_LDB(dst, b, h) do { _Pragma("unroll") for (int n = 0; n < 2; ++n) _Pragma("unroll") for (int k = 0; k < 2; ++k) dst[n][k] = *(const LAS bf16x8*)(lds + PG8_SB(b, h) + boff + n * 2048 + k * 1024); } while (0)
; #define PG8_BAR __builtin_amdgcn_s_barrier()
; template <class Epi, class Pre, bool AG = false>
; __device__ __forceinline__ void gemm_phase(LAS unsigned char* lds, const Gemm g, const StaticOrder& S, const Epi& E, const Pre& P) {
;     ...
;         const bool has_next = S.next(ui + 1, nxt);
;         const char* nA = has_next ? (const char*)g.A + (size_t)nxt.pm * tstepA : cA; const char* nB = has_next ? (const char*)g.Bt + (size_t)nxt.pn * tstep : cB;
;         for (int t = 0; t < nt; t += 2) {
;             const bool last = (t == nt - 2);
;             const char* a1 = cA + (size_t)(t + 1) * kstepA;
;             const char* a2 = last ? nA : cA + (size_t)(t + 2) * kstepA; const char* b2 = last ? nB : cB + (size_t)(t + 2) * kstep;
;             const char* a3 = a2 + kstepA; const char* b3 = b2 + kstep;
;             if constexpr (Epi::MIDK) { if (t == E.midk_t) E.mid(acc, cur, ui, wr, wc, fr, fq); }
;             PG8_LDB(B0, 0, 0); PG8_LDB(B1, 0, 1); PG8_SCHED; PG8_LDA(At, 0, 0); PG8_STAGE(PG8_SA(1, 1), a1 + hstepA, voffA);
;             PG8_WAIT_V(8); PG8_WAIT_L(0); PG8_BAR; PG8_MMA(0, 0, At, B0); PG8_MMA(0, 1, At, B1); PG8_BAR; PG8_SCHED;
;             PG8_LDA(At, 0, 1); PG8_STAGE(PG8_SB(0, 0), b2, voffB); PG8_STAGE(PG8_SB(0, 1), b2 + hstep, voffB); PG8_STAGE(PG8_SA(0, 0), a2, voffA);
;             PG8_WAIT_V(8); PG8_WAIT_L(0); PG8_BAR; PG8_MMA(1, 0, At, B0); PG8_MMA(1, 1, At, B1); PG8_BAR; PG8_SCHED;
;             PG8_LDB(B0, 1, 0); PG8_LDB(B1, 1, 1); PG8_SCHED; PG8_LDA(At, 1, 0); PG8_STAGE(PG8_SA(0, 1), a2 + hstepA, voffA);
;             PG8_WAIT_V(8); PG8_WAIT_L(0); PG8_BAR; PG8_MMA(0, 0, At, B0); PG8_MMA(0, 1, At, B1); PG8_BAR; PG8_SCHED;
.LBB0_478:
	s_ashr_i32 s71, s70, 31
	s_lshl_b64 s[12:13], s[70:71], 19
	s_add_u32 s78, s0, s12
	s_addc_u32 s79, s1, s13
	s_and_b64 s[12:13], s[8:9], exec
	s_cselect_b32 s12, s79, s11
	s_cselect_b32 s13, s78, s10
	s_ashr_i32 s45, s44, 31
	s_lshl_b64 s[56:57], s[44:45], 19
	s_add_u32 s94, s30, s56
	s_addc_u32 s95, s31, s57
	s_and_b64 s[56:57], s[8:9], exec
	s_cselect_b32 s45, s95, s55
	s_cselect_b32 s71, s94, s54
	s_add_u32 s10, s10, 0x40080
	s_addc_u32 s11, s11, 0
	s_add_u32 s85, s54, 0x100
	s_addc_u32 s86, s55, 0
	s_mov_b32 s87, -2
	s_waitcnt lgkmcnt(0)
	s_add_u32 s14, s10, 0xfffc0080
	s_addc_u32 s21, s11, -1
	s_add_i32 vcc_lo, 0, 0x10000
	s_cmp_eq_u32 s87, 12
	s_cselect_b32 s57, s12, s21
	s_cselect_b32 s56, s13, s14
	s_cselect_b32 s55, s45, s86
	s_cselect_b32 s54, s71, s85
	s_add_i32 s14, 0, 0x14000
	v_add_u32_e32 v152, vcc_lo, v164
	v_add_u32_e32 v170, s14, v164
	ds_read_b128 v[130:133], v152
	ds_read_b128 v[134:137], v152 offset:1024
	ds_read_b128 v[148:151], v152 offset:2048
	ds_read_b128 v[152:155], v152 offset:3072
	ds_read_b128 v[156:159], v170
	ds_read_b128 v[160:163], v170 offset:1024
	ds_read_b128 v[166:169], v170 offset:2048
	ds_read_b128 v[170:173], v170 offset:3072
	v_lshl_add_u64 v[182:183], s[10:11], 0, v[0:1]
	s_add_i32 m0, s49, 0xc000
	ds_read_b128 v[174:177], v165
	ds_read_b128 v[178:181], v165 offset:1024
	ds_read_b128 v[188:191], v165 offset:2048
	ds_read_b128 v[194:197], v165 offset:3072
	ds_read_b128 v[198:201], v165 offset:4096
	ds_read_b128 v[202:205], v165 offset:5120
	ds_read_b128 v[206:209], v165 offset:6144
	ds_read_b128 v[210:213], v165 offset:7168
	global_load_lds_dwordx4 v[182:183], off
	v_lshl_add_u64 v[182:183], s[10:11], 0, v[146:147]
	s_add_i32 m0, s49, 0xe000
	s_nop 0
	global_load_lds_dwordx4 v[182:183], off
	s_waitcnt vmcnt(8)
	s_waitcnt lgkmcnt(0)
	s_barrier
	s_setprio 1
	s_waitcnt lgkmcnt(0)
	v_mfma_f32_16x16x32_bf16 v[126:129], v[130:133], v[174:177], 0
	v_mfma_f32_16x16x32_bf16 v[122:125], v[148:151], v[174:177], 0
	v_mfma_f32_16x16x32_bf16 v[110:113], v[130:133], v[188:191], 0
	v_mfma_f32_16x16x32_bf16 v[106:109], v[148:151], v[188:191], 0
	v_mfma_f32_16x16x32_bf16 v[94:97], v[130:133], v[198:201], 0
	v_mfma_f32_16x16x32_bf16 v[90:93], v[148:151], v[198:201], 0
	v_mfma_f32_16x16x32_bf16 v[78:81], v[130:133], v[206:209], 0
	v_mfma_f32_16x16x32_bf16 v[74:77], v[148:151], v[206:209], 0
	v_mfma_f32_16x16x32_bf16 v[126:129], v[134:137], v[178:181], v[126:129]
	v_mfma_f32_16x16x32_bf16 v[122:125], v[152:155], v[178:181], v[122:125]
	v_mfma_f32_16x16x32_bf16 v[110:113], v[134:137], v[194:197], v[110:113]
	v_mfma_f32_16x16x32_bf16 v[106:109], v[152:155], v[194:197], v[106:109]
	v_mfma_f32_16x16x32_bf16 v[94:97], v[134:137], v[202:205], v[94:97]
	v_mfma_f32_16x16x32_bf16 v[90:93], v[152:155], v[202:205], v[90:93]
	v_mfma_f32_16x16x32_bf16 v[78:81], v[134:137], v[210:213], v[78:81]
	v_mfma_f32_16x16x32_bf16 v[74:77], v[152:155], v[210:213], v[74:77]
	s_setprio 0
	s_setprio 1
	v_mfma_f32_16x16x32_bf16 v[118:121], v[156:159], v[174:177], 0
	v_mfma_f32_16x16x32_bf16 v[114:117], v[166:169], v[174:177], 0
	v_mfma_f32_16x16x32_bf16 v[102:105], v[156:159], v[188:191], 0
	v_mfma_f32_16x16x32_bf16 v[98:101], v[166:169], v[188:191], 0
	v_mfma_f32_16x16x32_bf16 v[86:89], v[156:159], v[198:201], 0
	v_mfma_f32_16x16x32_bf16 v[82:85], v[166:169], v[198:201], 0
	v_mfma_f32_16x16x32_bf16 v[70:73], v[156:159], v[206:209], 0
	v_mfma_f32_16x16x32_bf16 v[66:69], v[166:169], v[206:209], 0
	v_mfma_f32_16x16x32_bf16 v[118:121], v[160:163], v[178:181], v[118:121]
	v_mfma_f32_16x16x32_bf16 v[114:117], v[170:173], v[178:181], v[114:117]
	v_mfma_f32_16x16x32_bf16 v[102:105], v[160:163], v[194:197], v[102:105]
	v_mfma_f32_16x16x32_bf16 v[98:101], v[170:173], v[194:197], v[98:101]
	v_mfma_f32_16x16x32_bf16 v[86:89], v[160:163], v[202:205], v[86:89]
	v_mfma_f32_16x16x32_bf16 v[82:85], v[170:173], v[202:205], v[82:85]
	v_mfma_f32_16x16x32_bf16 v[70:73], v[160:163], v[210:213], v[70:73]
	v_mfma_f32_16x16x32_bf16 v[66:69], v[170:173], v[210:213], v[66:69]
	s_setprio 0
	s_barrier
	s_add_i32 s21, vcc_lo, s48
	v_lshl_add_u64 v[182:183], s[54:55], 0, v[142:143]
	s_mov_b32 m0, s21
	ds_read_b128 v[174:177], v165 offset:16384
	ds_read_b128 v[178:181], v165 offset:17408
	ds_read_b128 v[188:191], v165 offset:18432
	ds_read_b128 v[194:197], v165 offset:19456
	ds_read_b128 v[198:201], v165 offset:20480
	ds_read_b128 v[202:205], v165 offset:21504
	ds_read_b128 v[206:209], v165 offset:22528
	ds_read_b128 v[210:213], v165 offset:23552
	global_load_lds_dwordx4 v[182:183], off
	s_add_i32 m0, s21, 0x2000
	s_add_u32 vcc_lo, s54, 0x40000
	v_lshl_add_u64 v[184:185], s[54:55], 0, v[138:139]
	s_addc_u32 vcc_hi, s55, 0
	s_add_i32 s14, s14, s48
	global_load_lds_dwordx4 v[184:185], off
	v_lshl_add_u64 v[186:187], vcc, 0, v[142:143]
	s_mov_b32 m0, s14
	v_lshl_add_u64 v[192:193], s[56:57], 0, v[140:141]
	global_load_lds_dwordx4 v[186:187], off
	v_lshl_add_u64 v[186:187], vcc, 0, v[138:139]
	s_add_i32 m0, s14, 0x2000
	s_nop 0
	global_load_lds_dwordx4 v[186:187], off
	v_lshl_add_u64 v[186:187], s[56:57], 0, v[144:145]
	s_mov_b32 m0, s49
	s_nop 0
	global_load_lds_dwordx4 v[186:187], off
	s_mov_b32 m0, s38
	s_nop 0
	global_load_lds_dwordx4 v[192:193], off
	s_waitcnt vmcnt(8)
	s_waitcnt lgkmcnt(0)
	s_barrier
; #define PG8_STAGE(bufoff, gbase, voff) do { _Pragma("unroll") for (int _i = 0; _i < 2; ++_i) \
;         __builtin_amdgcn_global_load_lds((const unsigned*)((const char*)(gbase) + (voff)[_i]), (LAS unsigned*)(lds + (bufoff) + ldsw + _i * 8192), 16, 0, 0); } while (0)
; #define PG8_LDA(dst, b, h) do { _Pragma("unroll") for (int m = 0; m < 4; ++m) _Pragma("unroll") for (int k = 0; k < 2; ++k) dst[m][k] = *(const LAS bf16x8*)(lds + PG8_SA(b, h) + aoff + m * 2048 + k * 1024); } while (0)
; #define PG8_LDB(dst, b, h) do { _Pragma("unroll") for (int n = 0; n < 2; ++n) _Pragma("unroll") for (int k = 0; k < 2; ++k) dst[n][k] = *(const LAS bf16x8*)(lds + PG8_SB(b, h) + boff + n * 2048 + k * 1024); } while (0)
; #define PG8_MMA(ai, bj, At, Bt) do { __builtin_amdgcn_s_setprio(1); _Pragma("unroll") for (int m = 0; m < 4; ++m) _Pragma("unroll") for (int n = 0; n < 2; ++n) _Pragma("unroll") for (int k = 0; k < 2; ++k) \
;         acc[ai][bj][m][n] = __builtin_amdgcn_mfma_f32_16x16x32_bf16(Bt[n][k], At[m][k], acc[ai][bj][m][n], 0, 0, 0); __builtin_amdgcn_s_setprio(0); } while (0)
; #define PG8_WAIT_V(n) asm volatile("s_waitcnt vmcnt(" #n ")" ::: "memory")
; template <class Epi, class Pre, bool AG = false>
; __device__ __forceinline__ void gemm_phase(LAS unsigned char* lds, const Gemm g, const StaticOrder& S, const Epi& E, const Pre& P) {
;     ...
;             PG8_LDB(B0, 0, 0); PG8_LDB(B1, 0, 1); PG8_SCHED; PG8_LDA(At, 0, 0); PG8_STAGE(PG8_SA(1, 1), a1 + hstepA, voffA);
;             PG8_WAIT_V(8); PG8_WAIT_L(0); PG8_BAR; PG8_MMA(0, 0, At, B0); PG8_MMA(0, 1, At, B1); PG8_BAR; PG8_SCHED;
;             PG8_LDA(At, 0, 1); PG8_STAGE(PG8_SB(0, 0), b2, voffB); PG8_STAGE(PG8_SB(0, 1), b2 + hstep, voffB); PG8_STAGE(PG8_SA(0, 0), a2, voffA);
;             PG8_WAIT_V(8); PG8_WAIT_L(0); PG8_BAR; PG8_MMA(1, 0, At, B0); PG8_MMA(1, 1, At, B1); PG8_BAR; PG8_SCHED;
;             PG8_LDB(B0, 1, 0); PG8_LDB(B1, 1, 1); PG8_SCHED; PG8_LDA(At, 1, 0); PG8_STAGE(PG8_SA(0, 1), a2 + hstepA, voffA);
;             PG8_WAIT_V(8); PG8_WAIT_L(0); PG8_BAR; PG8_MMA(0, 0, At, B0); PG8_MMA(0, 1, At, B1); PG8_BAR; PG8_SCHED;
;             PG8_LDA(At, 1, 1); PG8_STAGE(PG8_SB(1, 0), b3, voffB); PG8_STAGE(PG8_SB(1, 1), b3 + hstep, voffB); PG8_STAGE(PG8_SA(1, 0), a3, voffA);
;             PG8_WAIT_V(8); PG8_WAIT_L(0); PG8_BAR; PG8_MMA(1, 0, At, B0); PG8_MMA(1, 1, At, B1); PG8_BAR; PG8_SCHED;
	s_setprio 1
	s_waitcnt lgkmcnt(0)
	v_mfma_f32_16x16x32_bf16 v[62:65], v[130:133], v[174:177], 0
	v_mfma_f32_16x16x32_bf16 v[58:61], v[148:151], v[174:177], 0
	v_mfma_f32_16x16x32_bf16 v[46:49], v[130:133], v[188:191], 0
	v_mfma_f32_16x16x32_bf16 v[42:45], v[148:151], v[188:191], 0
	v_mfma_f32_16x16x32_bf16 v[30:33], v[130:133], v[198:201], 0
	v_mfma_f32_16x16x32_bf16 v[26:29], v[148:151], v[198:201], 0
	v_mfma_f32_16x16x32_bf16 v[14:17], v[130:133], v[206:209], 0
	v_mfma_f32_16x16x32_bf16 v[10:13], v[148:151], v[206:209], 0
	v_mfma_f32_16x16x32_bf16 v[62:65], v[134:137], v[178:181], v[62:65]
	v_mfma_f32_16x16x32_bf16 v[58:61], v[152:155], v[178:181], v[58:61]
	v_mfma_f32_16x16x32_bf16 v[46:49], v[134:137], v[194:197], v[46:49]
	v_mfma_f32_16x16x32_bf16 v[42:45], v[152:155], v[194:197], v[42:45]
	v_mfma_f32_16x16x32_bf16 v[30:33], v[134:137], v[202:205], v[30:33]
	v_mfma_f32_16x16x32_bf16 v[26:29], v[152:155], v[202:205], v[26:29]
	v_mfma_f32_16x16x32_bf16 v[14:17], v[134:137], v[210:213], v[14:17]
	v_mfma_f32_16x16x32_bf16 v[10:13], v[152:155], v[210:213], v[10:13]
	s_setprio 0
	s_setprio 1
	v_mfma_f32_16x16x32_bf16 v[54:57], v[156:159], v[174:177], 0
	v_mfma_f32_16x16x32_bf16 v[50:53], v[166:169], v[174:177], 0
	v_mfma_f32_16x16x32_bf16 v[38:41], v[156:159], v[188:191], 0
	v_mfma_f32_16x16x32_bf16 v[34:37], v[166:169], v[188:191], 0
	v_mfma_f32_16x16x32_bf16 v[22:25], v[156:159], v[198:201], 0
	v_mfma_f32_16x16x32_bf16 v[18:21], v[166:169], v[198:201], 0
	v_mfma_f32_16x16x32_bf16 v[6:9], v[156:159], v[206:209], 0
	v_mfma_f32_16x16x32_bf16 v[2:5], v[166:169], v[206:209], 0
	v_mfma_f32_16x16x32_bf16 v[54:57], v[160:163], v[178:181], v[54:57]
	v_mfma_f32_16x16x32_bf16 v[50:53], v[170:173], v[178:181], v[50:53]
	v_mfma_f32_16x16x32_bf16 v[38:41], v[160:163], v[194:197], v[38:41]
	v_mfma_f32_16x16x32_bf16 v[34:37], v[170:173], v[194:197], v[34:37]
	v_mfma_f32_16x16x32_bf16 v[22:25], v[160:163], v[202:205], v[22:25]
	v_mfma_f32_16x16x32_bf16 v[18:21], v[170:173], v[202:205], v[18:21]
	v_mfma_f32_16x16x32_bf16 v[6:9], v[160:163], v[210:213], v[6:9]
	v_mfma_f32_16x16x32_bf16 v[2:5], v[170:173], v[210:213], v[2:5]
	s_setprio 0
	s_barrier
	s_add_i32 s14, 0, 0x18000
	s_add_i32 s21, 0, 0x1c000
	v_add_u32_e32 v152, s14, v164
	v_add_u32_e32 v170, s21, v164
	ds_read_b128 v[130:133], v152
	ds_read_b128 v[134:137], v152 offset:1024
	ds_read_b128 v[148:151], v152 offset:2048
	ds_read_b128 v[152:155], v152 offset:3072
	ds_read_b128 v[156:159], v170
	ds_read_b128 v[160:163], v170 offset:1024
	ds_read_b128 v[166:169], v170 offset:2048
	ds_read_b128 v[170:173], v170 offset:3072
	s_add_u32 s56, s56, 0x40000
	s_addc_u32 s57, s57, 0
	s_mov_b32 m0, s58
	v_lshl_add_u64 v[214:215], s[56:57], 0, v[144:145]
	ds_read_b128 v[174:177], v165 offset:32768
	ds_read_b128 v[178:181], v165 offset:33792
	ds_read_b128 v[188:191], v165 offset:34816
	ds_read_b128 v[194:197], v165 offset:35840
	ds_read_b128 v[198:201], v165 offset:36864
	ds_read_b128 v[202:205], v165 offset:37888
	ds_read_b128 v[206:209], v165 offset:38912
	ds_read_b128 v[210:213], v165 offset:39936
	global_load_lds_dwordx4 v[214:215], off
	v_lshl_add_u64 v[214:215], s[56:57], 0, v[140:141]
	s_mov_b32 m0, s59
	s_nop 0
	global_load_lds_dwordx4 v[214:215], off
	s_waitcnt vmcnt(8)
	s_waitcnt lgkmcnt(0)
	s_barrier
	s_setprio 1
	s_waitcnt lgkmcnt(0)
	v_mfma_f32_16x16x32_bf16 v[126:129], v[130:133], v[174:177], v[126:129]
	v_mfma_f32_16x16x32_bf16 v[122:125], v[148:151], v[174:177], v[122:125]
	v_mfma_f32_16x16x32_bf16 v[110:113], v[130:133], v[188:191], v[110:113]
	v_mfma_f32_16x16x32_bf16 v[106:109], v[148:151], v[188:191], v[106:109]
	v_mfma_f32_16x16x32_bf16 v[94:97], v[130:133], v[198:201], v[94:97]
	v_mfma_f32_16x16x32_bf16 v[90:93], v[148:151], v[198:201], v[90:93]
	v_mfma_f32_16x16x32_bf16 v[78:81], v[130:133], v[206:209], v[78:81]
	v_mfma_f32_16x16x32_bf16 v[74:77], v[148:151], v[206:209], v[74:77]
	v_mfma_f32_16x16x32_bf16 v[126:129], v[134:137], v[178:181], v[126:129]
	v_mfma_f32_16x16x32_bf16 v[122:125], v[152:155], v[178:181], v[122:125]
	v_mfma_f32_16x16x32_bf16 v[110:113], v[134:137], v[194:197], v[110:113]
	v_mfma_f32_16x16x32_bf16 v[106:109], v[152:155], v[194:197], v[106:109]
	v_mfma_f32_16x16x32_bf16 v[94:97], v[134:137], v[202:205], v[94:97]
	v_mfma_f32_16x16x32_bf16 v[90:93], v[152:155], v[202:205], v[90:93]
	v_mfma_f32_16x16x32_bf16 v[78:81], v[134:137], v[210:213], v[78:81]
	v_mfma_f32_16x16x32_bf16 v[74:77], v[152:155], v[210:213], v[74:77]
	s_setprio 0
	s_setprio 1
	v_mfma_f32_16x16x32_bf16 v[118:121], v[156:159], v[174:177], v[118:121]
	v_mfma_f32_16x16x32_bf16 v[114:117], v[166:169], v[174:177], v[114:117]
	v_mfma_f32_16x16x32_bf16 v[102:105], v[156:159], v[188:191], v[102:105]
	v_mfma_f32_16x16x32_bf16 v[98:101], v[166:169], v[188:191], v[98:101]
	v_mfma_f32_16x16x32_bf16 v[86:89], v[156:159], v[198:201], v[86:89]
	v_mfma_f32_16x16x32_bf16 v[82:85], v[166:169], v[198:201], v[82:85]
	v_mfma_f32_16x16x32_bf16 v[70:73], v[156:159], v[206:209], v[70:73]
	v_mfma_f32_16x16x32_bf16 v[66:69], v[166:169], v[206:209], v[66:69]
	v_mfma_f32_16x16x32_bf16 v[118:121], v[160:163], v[178:181], v[118:121]
	v_mfma_f32_16x16x32_bf16 v[114:117], v[170:173], v[178:181], v[114:117]
	v_mfma_f32_16x16x32_bf16 v[102:105], v[160:163], v[194:197], v[102:105]
	v_mfma_f32_16x16x32_bf16 v[98:101], v[170:173], v[194:197], v[98:101]
	v_mfma_f32_16x16x32_bf16 v[86:89], v[160:163], v[202:205], v[86:89]
	v_mfma_f32_16x16x32_bf16 v[82:85], v[170:173], v[202:205], v[82:85]
	v_mfma_f32_16x16x32_bf16 v[70:73], v[160:163], v[210:213], v[70:73]
	v_mfma_f32_16x16x32_bf16 v[66:69], v[170:173], v[210:213], v[66:69]
	s_setprio 0
	s_barrier
; #define PG8_STAGE(bufoff, gbase, voff) do { _Pragma("unroll") for (int _i = 0; _i < 2; ++_i) \
;         __builtin_amdgcn_global_load_lds((const unsigned*)((const char*)(gbase) + (voff)[_i]), (LAS unsigned*)(lds + (bufoff) + ldsw + _i * 8192), 16, 0, 0); } while (0)
; #define PG8_LDA(dst, b, h) do { _Pragma("unroll") for (int m = 0; m < 4; ++m) _Pragma("unroll") for (int k = 0; k < 2; ++k) dst[m][k] = *(const LAS bf16x8*)(lds + PG8_SA(b, h) + aoff + m * 2048 + k * 1024); } while (0)
; #define PG8_LDB(dst, b, h) do { _Pragma("unroll") for (int n = 0; n < 2; ++n) _Pragma("unroll") for (int k = 0; k < 2; ++k) dst[n][k] = *(const LAS bf16x8*)(lds + PG8_SB(b, h) + boff + n * 2048 + k * 1024); } while (0)
; #define PG8_MMA(ai, bj, At, Bt) do { __builtin_amdgcn_s_setprio(1); _Pragma("unroll") for (int m = 0; m < 4; ++m) _Pragma("unroll") for (int n = 0; n < 2; ++n) _Pragma("unroll") for (int k = 0; k < 2; ++k) \
;         acc[ai][bj][m][n] = __builtin_amdgcn_mfma_f32_16x16x32_bf16(Bt[n][k], At[m][k], acc[ai][bj][m][n], 0, 0, 0); __builtin_amdgcn_s_setprio(0); } while (0)
; #define PG8_WAIT_V(n) asm volatile("s_waitcnt vmcnt(" #n ")" ::: "memory")
; #define PG8_WAIT_L(n) asm volatile("s_waitcnt lgkmcnt(" #n ")" ::: "memory")
; #define PG8_BAR __builtin_amdgcn_s_barrier()
; #define PG8_SCHED __builtin_amdgcn_sched_barrier(0)
; template <class Epi, class Pre, bool AG = false>
; __device__ __forceinline__ void gemm_phase(LAS unsigned char* lds, const Gemm g, const StaticOrder& S, const Epi& E, const Pre& P) {
;     ...
;             PG8_LDB(B0, 1, 0); PG8_LDB(B1, 1, 1); PG8_SCHED; PG8_LDA(At, 1, 0); PG8_STAGE(PG8_SA(0, 1), a2 + hstepA, voffA);
;             PG8_WAIT_V(8); PG8_WAIT_L(0); PG8_BAR; PG8_MMA(0, 0, At, B0); PG8_MMA(0, 1, At, B1); PG8_BAR; PG8_SCHED;
;             PG8_LDA(At, 1, 1); PG8_STAGE(PG8_SB(1, 0), b3, voffB); PG8_STAGE(PG8_SB(1, 1), b3 + hstep, voffB); PG8_STAGE(PG8_SA(1, 0), a3, voffA);
;             PG8_WAIT_V(8); PG8_WAIT_L(0); PG8_BAR; PG8_MMA(1, 0, At, B0); PG8_MMA(1, 1, At, B1); PG8_BAR; PG8_SCHED;
;         }
	s_add_i32 s14, s14, s48
	v_lshl_add_u64 v[182:183], v[182:183], 0, s[66:67]
	s_mov_b32 m0, s14
	ds_read_b128 v[174:177], v165 offset:49152
	ds_read_b128 v[178:181], v165 offset:50176
	ds_read_b128 v[188:191], v165 offset:51200
	ds_read_b128 v[194:197], v165 offset:52224
	ds_read_b128 v[198:201], v165 offset:53248
	ds_read_b128 v[202:205], v165 offset:54272
	ds_read_b128 v[206:209], v165 offset:55296
	ds_read_b128 v[210:213], v165 offset:56320
	global_load_lds_dwordx4 v[182:183], off
	s_add_i32 m0, s14, 0x2000
	s_add_u32 s54, s54, 0x40080
	v_lshl_add_u64 v[182:183], v[184:185], 0, s[66:67]
	s_addc_u32 s55, s55, 0
	s_add_i32 s14, s21, s48
	global_load_lds_dwordx4 v[182:183], off
	v_lshl_add_u64 v[182:183], s[54:55], 0, v[142:143]
	s_mov_b32 m0, s14
	s_nop 0
	global_load_lds_dwordx4 v[182:183], off
	v_lshl_add_u64 v[182:183], s[54:55], 0, v[138:139]
	s_add_i32 m0, s14, 0x2000
	s_nop 0
	global_load_lds_dwordx4 v[182:183], off
	v_lshl_add_u64 v[182:183], v[186:187], 0, s[66:67]
	s_mov_b32 m0, s53
	s_nop 0
	global_load_lds_dwordx4 v[182:183], off
	v_lshl_add_u64 v[182:183], v[192:193], 0, s[66:67]
	s_mov_b32 m0, s60
	s_nop 0
	global_load_lds_dwordx4 v[182:183], off
	s_waitcnt vmcnt(8)
	s_waitcnt lgkmcnt(0)
	s_barrier
	s_setprio 1
	s_waitcnt lgkmcnt(0)
	v_mfma_f32_16x16x32_bf16 v[62:65], v[130:133], v[174:177], v[62:65]
	v_mfma_f32_16x16x32_bf16 v[58:61], v[148:151], v[174:177], v[58:61]
	v_mfma_f32_16x16x32_bf16 v[46:49], v[130:133], v[188:191], v[46:49]
	v_mfma_f32_16x16x32_bf16 v[42:45], v[148:151], v[188:191], v[42:45]
	v_mfma_f32_16x16x32_bf16 v[30:33], v[130:133], v[198:201], v[30:33]
	v_mfma_f32_16x16x32_bf16 v[26:29], v[148:151], v[198:201], v[26:29]
	v_mfma_f32_16x16x32_bf16 v[14:17], v[130:133], v[206:209], v[14:17]
	v_mfma_f32_16x16x32_bf16 v[10:13], v[148:151], v[206:209], v[10:13]
	v_mfma_f32_16x16x32_bf16 v[62:65], v[134:137], v[178:181], v[62:65]
	v_mfma_f32_16x16x32_bf16 v[58:61], v[152:155], v[178:181], v[58:61]
	v_mfma_f32_16x16x32_bf16 v[46:49], v[134:137], v[194:197], v[46:49]
	v_mfma_f32_16x16x32_bf16 v[42:45], v[152:155], v[194:197], v[42:45]
	v_mfma_f32_16x16x32_bf16 v[30:33], v[134:137], v[202:205], v[30:33]
	v_mfma_f32_16x16x32_bf16 v[26:29], v[152:155], v[202:205], v[26:29]
	v_mfma_f32_16x16x32_bf16 v[14:17], v[134:137], v[210:213], v[14:17]
	v_mfma_f32_16x16x32_bf16 v[10:13], v[152:155], v[210:213], v[10:13]
	s_setprio 0
	s_setprio 1
	v_mfma_f32_16x16x32_bf16 v[54:57], v[156:159], v[174:177], v[54:57]
	v_mfma_f32_16x16x32_bf16 v[50:53], v[166:169], v[174:177], v[50:53]
	v_mfma_f32_16x16x32_bf16 v[38:41], v[156:159], v[188:191], v[38:41]
	v_mfma_f32_16x16x32_bf16 v[34:37], v[166:169], v[188:191], v[34:37]
	v_mfma_f32_16x16x32_bf16 v[22:25], v[156:159], v[198:201], v[22:25]
	v_mfma_f32_16x16x32_bf16 v[18:21], v[166:169], v[198:201], v[18:21]
	v_mfma_f32_16x16x32_bf16 v[6:9], v[156:159], v[206:209], v[6:9]
	v_mfma_f32_16x16x32_bf16 v[2:5], v[166:169], v[206:209], v[2:5]
	v_mfma_f32_16x16x32_bf16 v[54:57], v[160:163], v[178:181], v[54:57]
	v_mfma_f32_16x16x32_bf16 v[50:53], v[170:173], v[178:181], v[50:53]
	v_mfma_f32_16x16x32_bf16 v[38:41], v[160:163], v[194:197], v[38:41]
	v_mfma_f32_16x16x32_bf16 v[34:37], v[170:173], v[194:197], v[34:37]
	v_mfma_f32_16x16x32_bf16 v[22:25], v[160:163], v[202:205], v[22:25]
	v_mfma_f32_16x16x32_bf16 v[18:21], v[170:173], v[202:205], v[18:21]
	v_mfma_f32_16x16x32_bf16 v[6:9], v[160:163], v[210:213], v[6:9]
	v_mfma_f32_16x16x32_bf16 v[2:5], v[170:173], v[210:213], v[2:5]
	s_setprio 0
	s_barrier
	s_add_i32 s87, s87, 2
	s_add_u32 s10, s10, 0x100
	s_addc_u32 s11, s11, 0
	s_add_u32 s85, s85, 0x100
	s_addc_u32 s86, s86, 0
	s_cmp_gt_u32 s87, 13
	s_cbranch_scc0 .LBB0_479
	s_branch .Lpeel_ple_after

; #define PG8_STAGE(bufoff, gbase, voff) do { _Pragma("unroll") for (int _i = 0; _i < 2; ++_i) \
;         __builtin_amdgcn_global_load_lds((const unsigned*)((const char*)(gbase) + (voff)[_i]), (LAS unsigned*)(lds + (bufoff) + ldsw + _i * 8192), 16, 0, 0); } while (0)
; #define PG8_LDA(dst, b, h) do { _Pragma("unroll") for (int m = 0; m < 4; ++m) _Pragma("unroll") for (int k = 0; k < 2; ++k) dst[m][k] = *(const LAS bf16x8*)(lds + PG8_SA(b, h) + aoff + m * 2048 + k * 1024); } while (0)
; #define PG8_LDB(dst, b, h) do { _Pragma("unroll") for (int n = 0; n < 2; ++n) _Pragma("unroll") for (int k = 0; k < 2; ++k) dst[n][k] = *(const LAS bf16x8*)(lds + PG8_SB(b, h) + boff + n * 2048 + k * 1024); } while (0)
; #define PG8_BAR __builtin_amdgcn_s_barrier()
; template <class Epi, class Pre, bool AG = false>
; __device__ __forceinline__ void gemm_phase(LAS unsigned char* lds, const Gemm g, const StaticOrder& S, const Epi& E, const Pre& P) {
;     ...
;         const bool has_next = S.next(ui + 1, nxt);
;         const char* nA = has_next ? (const char*)g.A + (size_t)nxt.pm * tstepA : cA; const char* nB = has_next ? (const char*)g.Bt + (size_t)nxt.pn * tstep : cB;
;         for (int t = 0; t < nt; t += 2) {
;             const bool last = (t == nt - 2);
;             const char* a1 = cA + (size_t)(t + 1) * kstepA;
;             const char* a2 = last ? nA : cA + (size_t)(t + 2) * kstepA; const char* b2 = last ? nB : cB + (size_t)(t + 2) * kstep;
;             const char* a3 = a2 + kstepA; const char* b3 = b2 + kstep;
;             if constexpr (Epi::MIDK) { if (t == E.midk_t) E.mid(acc, cur, ui, wr, wc, fr, fq); }
;             PG8_LDB(B0, 0, 0); PG8_LDB(B1, 0, 1); PG8_SCHED; PG8_LDA(At, 0, 0); PG8_STAGE(PG8_SA(1, 1), a1 + hstepA, voffA);
;             PG8_WAIT_V(8); PG8_WAIT_L(0); PG8_BAR; PG8_MMA(0, 0, At, B0); PG8_MMA(0, 1, At, B1); PG8_BAR; PG8_SCHED;
;             PG8_LDA(At, 0, 1); PG8_STAGE(PG8_SB(0, 0), b2, voffB); PG8_STAGE(PG8_SB(0, 1), b2 + hstep, voffB); PG8_STAGE(PG8_SA(0, 0), a2, voffA);
;             PG8_WAIT_V(8); PG8_WAIT_L(0); PG8_BAR; PG8_MMA(1, 0, At, B0); PG8_MMA(1, 1, At, B1); PG8_BAR; PG8_SCHED;
;             PG8_LDB(B0, 1, 0); PG8_LDB(B1, 1, 1); PG8_SCHED; PG8_LDA(At, 1, 0); PG8_STAGE(PG8_SA(0, 1), a2 + hstepA, voffA);
;             PG8_WAIT_V(8); PG8_WAIT_L(0); PG8_BAR; PG8_MMA(0, 0, At, B0); PG8_MMA(0, 1, At, B1); PG8_BAR; PG8_SCHED;
.LBB0_578:
	s_ashr_i32 s29, s28, 31
	s_lshl_b64 s[12:13], s[28:29], 19
	s_add_u32 s42, s20, s12
	s_addc_u32 s43, s24, s13
	s_and_b64 s[12:13], s[8:9], exec
	s_cselect_b32 s12, s43, s47
	s_cselect_b32 s13, s42, s46
	s_ashr_i32 s27, s26, 31
	s_lshl_b64 s[44:45], s[26:27], 19
	s_add_u32 s44, s25, s44
	s_addc_u32 s45, s30, s45
	s_and_b64 s[56:57], s[8:9], exec
	s_cselect_b32 s27, s45, s55
	s_cselect_b32 s29, s44, s54
	s_add_u32 s46, s46, 0x40080
	s_addc_u32 s47, s47, 0
	s_add_u32 s78, s54, 0x100
	s_addc_u32 s79, s55, 0
	s_mov_b32 s84, -2
	s_add_u32 s54, s46, 0xfffc0080
	s_addc_u32 s55, s47, -1
	s_add_i32 s85, 0, 0x10000
	s_cmp_eq_u32 s84, 12
	s_cselect_b32 s57, s12, s55
	s_cselect_b32 s56, s13, s54
	v_add_u32_e32 v144, s85, v146
	s_cselect_b32 s55, s27, s79
	s_cselect_b32 s54, s29, s78
	s_add_i32 s94, 0, 0x14000
	ds_read_b128 v[140:143], v144
	ds_read_b128 v[148:151], v144 offset:1024
	ds_read_b128 v[152:155], v144 offset:2048
	ds_read_b128 v[156:159], v144 offset:3072
	v_add_u32_e32 v144, s94, v146
	ds_read_b128 v[160:163], v144
	ds_read_b128 v[164:167], v144 offset:1024
	ds_read_b128 v[168:171], v144 offset:2048
	ds_read_b128 v[172:175], v144 offset:3072
	v_lshl_add_u64 v[144:145], s[46:47], 0, v[0:1]
	s_add_i32 m0, s38, 0xc000
	ds_read_b128 v[194:197], v147
	ds_read_b128 v[198:201], v147 offset:1024
	ds_read_b128 v[202:205], v147 offset:2048
	ds_read_b128 v[206:209], v147 offset:3072
	ds_read_b128 v[210:213], v147 offset:4096
	ds_read_b128 v[214:217], v147 offset:5120
	ds_read_b128 v[218:221], v147 offset:6144
	ds_read_b128 v[222:225], v147 offset:7168
	global_load_lds_dwordx4 v[144:145], off
	v_lshl_add_u64 v[144:145], s[46:47], 0, v[138:139]
	s_add_i32 m0, s38, 0xe000
	s_nop 0
	global_load_lds_dwordx4 v[144:145], off
	s_waitcnt vmcnt(8)
	s_waitcnt lgkmcnt(0)
	s_barrier
	s_setprio 1
	s_waitcnt lgkmcnt(0)
	v_mfma_f32_16x16x32_bf16 v[126:129], v[140:143], v[194:197], 0
	v_mfma_f32_16x16x32_bf16 v[122:125], v[152:155], v[194:197], 0
	v_mfma_f32_16x16x32_bf16 v[110:113], v[140:143], v[202:205], 0
	v_mfma_f32_16x16x32_bf16 v[106:109], v[152:155], v[202:205], 0
	v_mfma_f32_16x16x32_bf16 v[94:97], v[140:143], v[210:213], 0
	v_mfma_f32_16x16x32_bf16 v[90:93], v[152:155], v[210:213], 0
	v_mfma_f32_16x16x32_bf16 v[78:81], v[140:143], v[218:221], 0
	v_mfma_f32_16x16x32_bf16 v[74:77], v[152:155], v[218:221], 0
	v_mfma_f32_16x16x32_bf16 v[126:129], v[148:151], v[198:201], v[126:129]
	v_mfma_f32_16x16x32_bf16 v[122:125], v[156:159], v[198:201], v[122:125]
	v_mfma_f32_16x16x32_bf16 v[110:113], v[148:151], v[206:209], v[110:113]
	v_mfma_f32_16x16x32_bf16 v[106:109], v[156:159], v[206:209], v[106:109]
	v_mfma_f32_16x16x32_bf16 v[94:97], v[148:151], v[214:217], v[94:97]
	v_mfma_f32_16x16x32_bf16 v[90:93], v[156:159], v[214:217], v[90:93]
	v_mfma_f32_16x16x32_bf16 v[78:81], v[148:151], v[222:225], v[78:81]
	v_mfma_f32_16x16x32_bf16 v[74:77], v[156:159], v[222:225], v[74:77]
	s_setprio 0
	s_setprio 1
	v_mfma_f32_16x16x32_bf16 v[118:121], v[160:163], v[194:197], 0
	v_mfma_f32_16x16x32_bf16 v[114:117], v[168:171], v[194:197], 0
	v_mfma_f32_16x16x32_bf16 v[102:105], v[160:163], v[202:205], 0
	v_mfma_f32_16x16x32_bf16 v[98:101], v[168:171], v[202:205], 0
	v_mfma_f32_16x16x32_bf16 v[86:89], v[160:163], v[210:213], 0
	v_mfma_f32_16x16x32_bf16 v[82:85], v[168:171], v[210:213], 0
	v_mfma_f32_16x16x32_bf16 v[70:73], v[160:163], v[218:221], 0
	v_mfma_f32_16x16x32_bf16 v[66:69], v[168:171], v[218:221], 0
	v_mfma_f32_16x16x32_bf16 v[118:121], v[164:167], v[198:201], v[118:121]
	v_mfma_f32_16x16x32_bf16 v[114:117], v[172:175], v[198:201], v[114:117]
	v_mfma_f32_16x16x32_bf16 v[102:105], v[164:167], v[206:209], v[102:105]
	v_mfma_f32_16x16x32_bf16 v[98:101], v[172:175], v[206:209], v[98:101]
	v_mfma_f32_16x16x32_bf16 v[86:89], v[164:167], v[214:217], v[86:89]
	v_mfma_f32_16x16x32_bf16 v[82:85], v[172:175], v[214:217], v[82:85]
	v_mfma_f32_16x16x32_bf16 v[70:73], v[164:167], v[222:225], v[70:73]
	v_mfma_f32_16x16x32_bf16 v[66:69], v[172:175], v[222:225], v[66:69]
	s_setprio 0
	s_barrier
	s_add_i32 s85, s85, s31
	v_lshl_add_u64 v[144:145], s[54:55], 0, v[134:135]
	s_mov_b32 m0, s85
	ds_read_b128 v[194:197], v147 offset:16384
	ds_read_b128 v[198:201], v147 offset:17408
	ds_read_b128 v[202:205], v147 offset:18432
	ds_read_b128 v[206:209], v147 offset:19456
	ds_read_b128 v[210:213], v147 offset:20480
	ds_read_b128 v[214:217], v147 offset:21504
	ds_read_b128 v[218:221], v147 offset:22528
	ds_read_b128 v[222:225], v147 offset:23552
	global_load_lds_dwordx4 v[144:145], off
	s_add_i32 m0, s85, 0x2000
	s_add_u32 s86, s54, 0x40000
	v_lshl_add_u64 v[176:177], s[54:55], 0, v[130:131]
	s_addc_u32 s87, s55, 0
	s_add_i32 s85, s94, s31
	global_load_lds_dwordx4 v[176:177], off
	v_lshl_add_u64 v[178:179], s[86:87], 0, v[134:135]
	s_mov_b32 m0, s85
	v_lshl_add_u64 v[180:181], s[56:57], 0, v[132:133]
	global_load_lds_dwordx4 v[178:179], off
	v_lshl_add_u64 v[178:179], s[86:87], 0, v[130:131]
	s_add_i32 m0, s85, 0x2000
	s_nop 0
	global_load_lds_dwordx4 v[178:179], off
	v_lshl_add_u64 v[178:179], s[56:57], 0, v[136:137]
	s_mov_b32 m0, s38
	s_nop 0
	global_load_lds_dwordx4 v[178:179], off
	s_mov_b32 m0, s48
	s_nop 0
	global_load_lds_dwordx4 v[180:181], off
	s_waitcnt vmcnt(8)
	s_waitcnt lgkmcnt(0)
	s_barrier
; #define PG8_STAGE(bufoff, gbase, voff) do { _Pragma("unroll") for (int _i = 0; _i < 2; ++_i) \
;         __builtin_amdgcn_global_load_lds((const unsigned*)((const char*)(gbase) + (voff)[_i]), (LAS unsigned*)(lds + (bufoff) + ldsw + _i * 8192), 16, 0, 0); } while (0)
; #define PG8_LDA(dst, b, h) do { _Pragma("unroll") for (int m = 0; m < 4; ++m) _Pragma("unroll") for (int k = 0; k < 2; ++k) dst[m][k] = *(const LAS bf16x8*)(lds + PG8_SA(b, h) + aoff + m * 2048 + k * 1024); } while (0)
; #define PG8_LDB(dst, b, h) do { _Pragma("unroll") for (int n = 0; n < 2; ++n) _Pragma("unroll") for (int k = 0; k < 2; ++k) dst[n][k] = *(const LAS bf16x8*)(lds + PG8_SB(b, h) + boff + n * 2048 + k * 1024); } while (0)
; #define PG8_MMA(ai, bj, At, Bt) do { __builtin_amdgcn_s_setprio(1); _Pragma("unroll") for (int m = 0; m < 4; ++m) _Pragma("unroll") for (int n = 0; n < 2; ++n) _Pragma("unroll") for (int k = 0; k < 2; ++k) \
;         acc[ai][bj][m][n] = __builtin_amdgcn_mfma_f32_16x16x32_bf16(Bt[n][k], At[m][k], acc[ai][bj][m][n], 0, 0, 0); __builtin_amdgcn_s_setprio(0); } while (0)
; #define PG8_WAIT_V(n) asm volatile("s_waitcnt vmcnt(" #n ")" ::: "memory")
; template <class Epi, class Pre, bool AG = false>
; __device__ __forceinline__ void gemm_phase(LAS unsigned char* lds, const Gemm g, const StaticOrder& S, const Epi& E, const Pre& P) {
;     ...
;             PG8_LDB(B0, 0, 0); PG8_LDB(B1, 0, 1); PG8_SCHED; PG8_LDA(At, 0, 0); PG8_STAGE(PG8_SA(1, 1), a1 + hstepA, voffA);
;             PG8_WAIT_V(8); PG8_WAIT_L(0); PG8_BAR; PG8_MMA(0, 0, At, B0); PG8_MMA(0, 1, At, B1); PG8_BAR; PG8_SCHED;
;             PG8_LDA(At, 0, 1); PG8_STAGE(PG8_SB(0, 0), b2, voffB); PG8_STAGE(PG8_SB(0, 1), b2 + hstep, voffB); PG8_STAGE(PG8_SA(0, 0), a2, voffA);
;             PG8_WAIT_V(8); PG8_WAIT_L(0); PG8_BAR; PG8_MMA(1, 0, At, B0); PG8_MMA(1, 1, At, B1); PG8_BAR; PG8_SCHED;
;             PG8_LDB(B0, 1, 0); PG8_LDB(B1, 1, 1); PG8_SCHED; PG8_LDA(At, 1, 0); PG8_STAGE(PG8_SA(0, 1), a2 + hstepA, voffA);
;             PG8_WAIT_V(8); PG8_WAIT_L(0); PG8_BAR; PG8_MMA(0, 0, At, B0); PG8_MMA(0, 1, At, B1); PG8_BAR; PG8_SCHED;
;             PG8_LDA(At, 1, 1); PG8_STAGE(PG8_SB(1, 0), b3, voffB); PG8_STAGE(PG8_SB(1, 1), b3 + hstep, voffB); PG8_STAGE(PG8_SA(1, 0), a3, voffA);
;             PG8_WAIT_V(8); PG8_WAIT_L(0); PG8_BAR; PG8_MMA(1, 0, At, B0); PG8_MMA(1, 1, At, B1); PG8_BAR; PG8_SCHED;
	s_setprio 1
	s_waitcnt lgkmcnt(0)
	v_mfma_f32_16x16x32_bf16 v[62:65], v[140:143], v[194:197], 0
	v_mfma_f32_16x16x32_bf16 v[58:61], v[152:155], v[194:197], 0
	v_mfma_f32_16x16x32_bf16 v[50:53], v[140:143], v[202:205], 0
	v_mfma_f32_16x16x32_bf16 v[42:45], v[152:155], v[202:205], 0
	v_mfma_f32_16x16x32_bf16 v[34:37], v[140:143], v[210:213], 0
	v_mfma_f32_16x16x32_bf16 v[26:29], v[152:155], v[210:213], 0
	v_mfma_f32_16x16x32_bf16 v[18:21], v[140:143], v[218:221], 0
	v_mfma_f32_16x16x32_bf16 v[10:13], v[152:155], v[218:221], 0
	v_mfma_f32_16x16x32_bf16 v[62:65], v[148:151], v[198:201], v[62:65]
	v_mfma_f32_16x16x32_bf16 v[58:61], v[156:159], v[198:201], v[58:61]
	v_mfma_f32_16x16x32_bf16 v[50:53], v[148:151], v[206:209], v[50:53]
	v_mfma_f32_16x16x32_bf16 v[42:45], v[156:159], v[206:209], v[42:45]
	v_mfma_f32_16x16x32_bf16 v[34:37], v[148:151], v[214:217], v[34:37]
	v_mfma_f32_16x16x32_bf16 v[26:29], v[156:159], v[214:217], v[26:29]
	v_mfma_f32_16x16x32_bf16 v[18:21], v[148:151], v[222:225], v[18:21]
	v_mfma_f32_16x16x32_bf16 v[10:13], v[156:159], v[222:225], v[10:13]
	s_setprio 0
	s_setprio 1
	v_mfma_f32_16x16x32_bf16 v[54:57], v[160:163], v[194:197], 0
	v_mfma_f32_16x16x32_bf16 v[46:49], v[168:171], v[194:197], 0
	v_mfma_f32_16x16x32_bf16 v[38:41], v[160:163], v[202:205], 0
	v_mfma_f32_16x16x32_bf16 v[30:33], v[168:171], v[202:205], 0
	v_mfma_f32_16x16x32_bf16 v[22:25], v[160:163], v[210:213], 0
	v_mfma_f32_16x16x32_bf16 v[14:17], v[168:171], v[210:213], 0
	v_mfma_f32_16x16x32_bf16 v[6:9], v[160:163], v[218:221], 0
	v_mfma_f32_16x16x32_bf16 v[2:5], v[168:171], v[218:221], 0
	v_mfma_f32_16x16x32_bf16 v[54:57], v[164:167], v[198:201], v[54:57]
	v_mfma_f32_16x16x32_bf16 v[46:49], v[172:175], v[198:201], v[46:49]
	v_mfma_f32_16x16x32_bf16 v[38:41], v[164:167], v[206:209], v[38:41]
	v_mfma_f32_16x16x32_bf16 v[30:33], v[172:175], v[206:209], v[30:33]
	v_mfma_f32_16x16x32_bf16 v[22:25], v[164:167], v[214:217], v[22:25]
	v_mfma_f32_16x16x32_bf16 v[14:17], v[172:175], v[214:217], v[14:17]
	v_mfma_f32_16x16x32_bf16 v[6:9], v[164:167], v[222:225], v[6:9]
	v_mfma_f32_16x16x32_bf16 v[2:5], v[172:175], v[222:225], v[2:5]
	s_setprio 0
	s_barrier
	s_add_i32 s85, 0, 0x18000
	s_add_i32 s86, 0, 0x1c000
	v_add_u32_e32 v156, s85, v146
	v_add_u32_e32 v172, s86, v146
	ds_read_b128 v[140:143], v156
	ds_read_b128 v[148:151], v156 offset:1024
	ds_read_b128 v[152:155], v156 offset:2048
	ds_read_b128 v[156:159], v156 offset:3072
	ds_read_b128 v[160:163], v172
	ds_read_b128 v[164:167], v172 offset:1024
	ds_read_b128 v[168:171], v172 offset:2048
	ds_read_b128 v[172:175], v172 offset:3072
	s_add_u32 s56, s56, 0x40000
	s_addc_u32 s57, s57, 0
	s_mov_b32 m0, s49
	v_lshl_add_u64 v[182:183], s[56:57], 0, v[136:137]
	ds_read_b128 v[194:197], v147 offset:32768
	ds_read_b128 v[198:201], v147 offset:33792
	ds_read_b128 v[202:205], v147 offset:34816
	ds_read_b128 v[206:209], v147 offset:35840
	ds_read_b128 v[210:213], v147 offset:36864
	ds_read_b128 v[214:217], v147 offset:37888
	ds_read_b128 v[218:221], v147 offset:38912
	ds_read_b128 v[222:225], v147 offset:39936
	global_load_lds_dwordx4 v[182:183], off
	v_lshl_add_u64 v[182:183], s[56:57], 0, v[132:133]
	s_mov_b32 m0, s53
	s_nop 0
	global_load_lds_dwordx4 v[182:183], off
	s_waitcnt vmcnt(8)
	s_waitcnt lgkmcnt(0)
	s_barrier
	s_setprio 1
	s_waitcnt lgkmcnt(0)
	v_mfma_f32_16x16x32_bf16 v[126:129], v[140:143], v[194:197], v[126:129]
	v_mfma_f32_16x16x32_bf16 v[122:125], v[152:155], v[194:197], v[122:125]
	v_mfma_f32_16x16x32_bf16 v[110:113], v[140:143], v[202:205], v[110:113]
	v_mfma_f32_16x16x32_bf16 v[106:109], v[152:155], v[202:205], v[106:109]
	v_mfma_f32_16x16x32_bf16 v[94:97], v[140:143], v[210:213], v[94:97]
	v_mfma_f32_16x16x32_bf16 v[90:93], v[152:155], v[210:213], v[90:93]
	v_mfma_f32_16x16x32_bf16 v[78:81], v[140:143], v[218:221], v[78:81]
	v_mfma_f32_16x16x32_bf16 v[74:77], v[152:155], v[218:221], v[74:77]
	v_mfma_f32_16x16x32_bf16 v[126:129], v[148:151], v[198:201], v[126:129]
	v_mfma_f32_16x16x32_bf16 v[122:125], v[156:159], v[198:201], v[122:125]
	v_mfma_f32_16x16x32_bf16 v[110:113], v[148:151], v[206:209], v[110:113]
	v_mfma_f32_16x16x32_bf16 v[106:109], v[156:159], v[206:209], v[106:109]
	v_mfma_f32_16x16x32_bf16 v[94:97], v[148:151], v[214:217], v[94:97]
	v_mfma_f32_16x16x32_bf16 v[90:93], v[156:159], v[214:217], v[90:93]
	v_mfma_f32_16x16x32_bf16 v[78:81], v[148:151], v[222:225], v[78:81]
	v_mfma_f32_16x16x32_bf16 v[74:77], v[156:159], v[222:225], v[74:77]
	s_setprio 0
	s_setprio 1
	v_mfma_f32_16x16x32_bf16 v[118:121], v[160:163], v[194:197], v[118:121]
	v_mfma_f32_16x16x32_bf16 v[114:117], v[168:171], v[194:197], v[114:117]
	v_mfma_f32_16x16x32_bf16 v[102:105], v[160:163], v[202:205], v[102:105]
	v_mfma_f32_16x16x32_bf16 v[98:101], v[168:171], v[202:205], v[98:101]
	v_mfma_f32_16x16x32_bf16 v[86:89], v[160:163], v[210:213], v[86:89]
	v_mfma_f32_16x16x32_bf16 v[82:85], v[168:171], v[210:213], v[82:85]
	v_mfma_f32_16x16x32_bf16 v[70:73], v[160:163], v[218:221], v[70:73]
	v_mfma_f32_16x16x32_bf16 v[66:69], v[168:171], v[218:221], v[66:69]
	v_mfma_f32_16x16x32_bf16 v[118:121], v[164:167], v[198:201], v[118:121]
	v_mfma_f32_16x16x32_bf16 v[114:117], v[172:175], v[198:201], v[114:117]
	v_mfma_f32_16x16x32_bf16 v[102:105], v[164:167], v[206:209], v[102:105]
	v_mfma_f32_16x16x32_bf16 v[98:101], v[172:175], v[206:209], v[98:101]
	v_mfma_f32_16x16x32_bf16 v[86:89], v[164:167], v[214:217], v[86:89]
	v_mfma_f32_16x16x32_bf16 v[82:85], v[172:175], v[214:217], v[82:85]
	v_mfma_f32_16x16x32_bf16 v[70:73], v[164:167], v[222:225], v[70:73]
	v_mfma_f32_16x16x32_bf16 v[66:69], v[172:175], v[222:225], v[66:69]
	s_setprio 0
	s_barrier
; #define PG8_STAGE(bufoff, gbase, voff) do { _Pragma("unroll") for (int _i = 0; _i < 2; ++_i) \
;         __builtin_amdgcn_global_load_lds((const unsigned*)((const char*)(gbase) + (voff)[_i]), (LAS unsigned*)(lds + (bufoff) + ldsw + _i * 8192), 16, 0, 0); } while (0)
; #define PG8_LDA(dst, b, h) do { _Pragma("unroll") for (int m = 0; m < 4; ++m) _Pragma("unroll") for (int k = 0; k < 2; ++k) dst[m][k] = *(const LAS bf16x8*)(lds + PG8_SA(b, h) + aoff + m * 2048 + k * 1024); } while (0)
; #define PG8_MMA(ai, bj, At, Bt) do { __builtin_amdgcn_s_setprio(1); _Pragma("unroll") for (int m = 0; m < 4; ++m) _Pragma("unroll") for (int n = 0; n < 2; ++n) _Pragma("unroll") for (int k = 0; k < 2; ++k) \
;         acc[ai][bj][m][n] = __builtin_amdgcn_mfma_f32_16x16x32_bf16(Bt[n][k], At[m][k], acc[ai][bj][m][n], 0, 0, 0); __builtin_amdgcn_s_setprio(0); } while (0)
; #define PG8_WAIT_V(n) asm volatile("s_waitcnt vmcnt(" #n ")" ::: "memory")
; #define PG8_WAIT_L(n) asm volatile("s_waitcnt lgkmcnt(" #n ")" ::: "memory")
; #define PG8_BAR __builtin_amdgcn_s_barrier()
; #define PG8_SCHED __builtin_amdgcn_sched_barrier(0)
; template <class Epi, class Pre, bool AG = false>
; __device__ __forceinline__ void gemm_phase(LAS unsigned char* lds, const Gemm g, const StaticOrder& S, const Epi& E, const Pre& P) {
;     ...
;             PG8_LDA(At, 1, 1); PG8_STAGE(PG8_SB(1, 0), b3, voffB); PG8_STAGE(PG8_SB(1, 1), b3 + hstep, voffB); PG8_STAGE(PG8_SA(1, 0), a3, voffA);
;             PG8_WAIT_V(8); PG8_WAIT_L(0); PG8_BAR; PG8_MMA(1, 0, At, B0); PG8_MMA(1, 1, At, B1); PG8_BAR; PG8_SCHED;
	s_add_i32 s56, s85, s31
	v_lshl_add_u64 v[144:145], v[144:145], 0, s[66:67]
	s_mov_b32 m0, s56
	ds_read_b128 v[194:197], v147 offset:49152
	ds_read_b128 v[198:201], v147 offset:50176
	ds_read_b128 v[202:205], v147 offset:51200
	ds_read_b128 v[206:209], v147 offset:52224
	ds_read_b128 v[210:213], v147 offset:53248
	ds_read_b128 v[214:217], v147 offset:54272
	ds_read_b128 v[218:221], v147 offset:55296
	ds_read_b128 v[222:225], v147 offset:56320
	global_load_lds_dwordx4 v[144:145], off
	s_add_i32 m0, s56, 0x2000
	s_add_u32 s54, s54, 0x40080
	v_lshl_add_u64 v[144:145], v[176:177], 0, s[66:67]
	s_addc_u32 s55, s55, 0
	s_add_i32 s56, s86, s31
	global_load_lds_dwordx4 v[144:145], off
	v_lshl_add_u64 v[144:145], s[54:55], 0, v[134:135]
	s_mov_b32 m0, s56
	s_nop 0
	global_load_lds_dwordx4 v[144:145], off
	v_lshl_add_u64 v[144:145], s[54:55], 0, v[130:131]
	s_add_i32 m0, s56, 0x2000
	s_nop 0
	global_load_lds_dwordx4 v[144:145], off
	v_lshl_add_u64 v[144:145], v[178:179], 0, s[66:67]
	s_mov_b32 m0, s60
	s_nop 0
	global_load_lds_dwordx4 v[144:145], off
	v_lshl_add_u64 v[144:145], v[180:181], 0, s[66:67]
	s_mov_b32 m0, s61
	s_nop 0
	global_load_lds_dwordx4 v[144:145], off
	s_waitcnt vmcnt(8)
	s_waitcnt lgkmcnt(0)
	s_barrier
	s_setprio 1
	s_waitcnt lgkmcnt(0)
	v_mfma_f32_16x16x32_bf16 v[62:65], v[140:143], v[194:197], v[62:65]
	v_mfma_f32_16x16x32_bf16 v[58:61], v[152:155], v[194:197], v[58:61]
	v_mfma_f32_16x16x32_bf16 v[50:53], v[140:143], v[202:205], v[50:53]
	v_mfma_f32_16x16x32_bf16 v[42:45], v[152:155], v[202:205], v[42:45]
	v_mfma_f32_16x16x32_bf16 v[34:37], v[140:143], v[210:213], v[34:37]
	v_mfma_f32_16x16x32_bf16 v[26:29], v[152:155], v[210:213], v[26:29]
	v_mfma_f32_16x16x32_bf16 v[18:21], v[140:143], v[218:221], v[18:21]
	v_mfma_f32_16x16x32_bf16 v[10:13], v[152:155], v[218:221], v[10:13]
	v_mfma_f32_16x16x32_bf16 v[62:65], v[148:151], v[198:201], v[62:65]
	v_mfma_f32_16x16x32_bf16 v[58:61], v[156:159], v[198:201], v[58:61]
	v_mfma_f32_16x16x32_bf16 v[50:53], v[148:151], v[206:209], v[50:53]
	v_mfma_f32_16x16x32_bf16 v[42:45], v[156:159], v[206:209], v[42:45]
	v_mfma_f32_16x16x32_bf16 v[34:37], v[148:151], v[214:217], v[34:37]
	v_mfma_f32_16x16x32_bf16 v[26:29], v[156:159], v[214:217], v[26:29]
	v_mfma_f32_16x16x32_bf16 v[18:21], v[148:151], v[222:225], v[18:21]
	v_mfma_f32_16x16x32_bf16 v[10:13], v[156:159], v[222:225], v[10:13]
	s_setprio 0
	s_setprio 1
	v_mfma_f32_16x16x32_bf16 v[54:57], v[160:163], v[194:197], v[54:57]
	v_mfma_f32_16x16x32_bf16 v[46:49], v[168:171], v[194:197], v[46:49]
	v_mfma_f32_16x16x32_bf16 v[38:41], v[160:163], v[202:205], v[38:41]
	v_mfma_f32_16x16x32_bf16 v[30:33], v[168:171], v[202:205], v[30:33]
	v_mfma_f32_16x16x32_bf16 v[22:25], v[160:163], v[210:213], v[22:25]
	v_mfma_f32_16x16x32_bf16 v[14:17], v[168:171], v[210:213], v[14:17]
	v_mfma_f32_16x16x32_bf16 v[6:9], v[160:163], v[218:221], v[6:9]
	v_mfma_f32_16x16x32_bf16 v[2:5], v[168:171], v[218:221], v[2:5]
	v_mfma_f32_16x16x32_bf16 v[54:57], v[164:167], v[198:201], v[54:57]
	v_mfma_f32_16x16x32_bf16 v[46:49], v[172:175], v[198:201], v[46:49]
	v_mfma_f32_16x16x32_bf16 v[38:41], v[164:167], v[206:209], v[38:41]
	v_mfma_f32_16x16x32_bf16 v[30:33], v[172:175], v[206:209], v[30:33]
	v_mfma_f32_16x16x32_bf16 v[22:25], v[164:167], v[214:217], v[22:25]
	v_mfma_f32_16x16x32_bf16 v[14:17], v[172:175], v[214:217], v[14:17]
	v_mfma_f32_16x16x32_bf16 v[6:9], v[164:167], v[222:225], v[6:9]
	v_mfma_f32_16x16x32_bf16 v[2:5], v[172:175], v[222:225], v[2:5]
	s_setprio 0
	s_barrier
	s_add_i32 s84, s84, 2
	s_add_u32 s46, s46, 0x100
	s_addc_u32 s47, s47, 0
	s_add_u32 s78, s78, 0x100
	s_addc_u32 s79, s79, 0
	s_cmp_gt_u32 s84, 13
	s_cbranch_scc0 .LBB0_579
	s_branch .Lpeel_win_after

; #define PG8_BAR __builtin_amdgcn_s_barrier()
; template <class Epi, class Pre, bool AG = false>
; __device__ __forceinline__ void gemm_phase(LAS unsigned char* lds, const Gemm g, const StaticOrder& S, const Epi& E, const Pre& P) {
;     ...
;         if (wr == 0) PG8_BAR;
.Lpeel_win_after:
	s_and_b64 vcc, exec, s[16:17]
	s_cbranch_vccz .LBB0_582
	s_barrier

; #define PG8_STAGE(bufoff, gbase, voff) do { _Pragma("unroll") for (int _i = 0; _i < 2; ++_i) \
;         __builtin_amdgcn_global_load_lds((const unsigned*)((const char*)(gbase) + (voff)[_i]), (LAS unsigned*)(lds + (bufoff) + ldsw + _i * 8192), 16, 0, 0); } while (0)
; #define PG8_LDA(dst, b, h) do { _Pragma("unroll") for (int m = 0; m < 4; ++m) _Pragma("unroll") for (int k = 0; k < 2; ++k) dst[m][k] = *(const LAS bf16x8*)(lds + PG8_SA(b, h) + aoff + m * 2048 + k * 1024); } while (0)
; #define PG8_LDB(dst, b, h) do { _Pragma("unroll") for (int n = 0; n < 2; ++n) _Pragma("unroll") for (int k = 0; k < 2; ++k) dst[n][k] = *(const LAS bf16x8*)(lds + PG8_SB(b, h) + boff + n * 2048 + k * 1024); } while (0)
; #define PG8_MMA(ai, bj, At, Bt) do { __builtin_amdgcn_s_setprio(1); _Pragma("unroll") for (int m = 0; m < 4; ++m) _Pragma("unroll") for (int n = 0; n < 2; ++n) _Pragma("unroll") for (int k = 0; k < 2; ++k) \
;         acc[ai][bj][m][n] = __builtin_amdgcn_mfma_f32_16x16x32_bf16(Bt[n][k], At[m][k], acc[ai][bj][m][n], 0, 0, 0); __builtin_amdgcn_s_setprio(0); } while (0)
; #define PG8_WAIT_V(n) asm volatile("s_waitcnt vmcnt(" #n ")" ::: "memory")
; #define PG8_WAIT_L(n) asm volatile("s_waitcnt lgkmcnt(" #n ")" ::: "memory")
; template <class Epi, class Pre, bool AG = false>
; __device__ __forceinline__ void gemm_phase(LAS unsigned char* lds, const Gemm g, const StaticOrder& S, const Epi& E, const Pre& P) {
;     ...
;         for (int t = 0; t < nt; t += 2) {
;             const bool last = (t == nt - 2);
;             const char* a1 = cA + (size_t)(t + 1) * kstepA;
;             const char* a2 = last ? nA : cA + (size_t)(t + 2) * kstepA; const char* b2 = last ? nB : cB + (size_t)(t + 2) * kstep;
;             const char* a3 = a2 + kstepA; const char* b3 = b2 + kstep;
;             if constexpr (Epi::MIDK) { if (t == E.midk_t) E.mid(acc, cur, ui, wr, wc, fr, fq); }
;             PG8_LDB(B0, 0, 0); PG8_LDB(B1, 0, 1); PG8_SCHED; PG8_LDA(At, 0, 0); PG8_STAGE(PG8_SA(1, 1), a1 + hstepA, voffA);
;             PG8_WAIT_V(8); PG8_WAIT_L(0); PG8_BAR; PG8_MMA(0, 0, At, B0); PG8_MMA(0, 1, At, B1); PG8_BAR; PG8_SCHED;
;             PG8_LDA(At, 0, 1); PG8_STAGE(PG8_SB(0, 0), b2, voffB); PG8_STAGE(PG8_SB(0, 1), b2 + hstep, voffB); PG8_STAGE(PG8_SA(0, 0), a2, voffA);
;             PG8_WAIT_V(8); PG8_WAIT_L(0); PG8_BAR; PG8_MMA(1, 0, At, B0); PG8_MMA(1, 1, At, B1); PG8_BAR; PG8_SCHED;
.LBB0_740:
	s_ashr_i32 s29, s28, 31
	s_lshl_b64 s[12:13], s[28:29], 13
	s_add_u32 s42, s0, s12
	s_addc_u32 s43, s1, s13
	s_and_b64 s[12:13], s[8:9], exec
	s_cselect_b32 s12, s43, s11
	s_cselect_b32 s13, s42, s10
	s_ashr_i32 s27, s26, 31
	s_lshl_b64 s[44:45], s[26:27], 18
	s_add_u32 s44, s30, s44
	s_addc_u32 s45, s31, s45
	s_and_b64 s[56:57], s[8:9], exec
	s_cselect_b32 s27, s45, s55
	s_cselect_b32 s29, s44, s54
	s_add_u32 vcc_lo, s54, 0x100
	s_addc_u32 vcc_hi, s55, 0
	s_mov_b32 s87, -2
	s_add_u32 s54, s10, 0x400000
	s_addc_u32 s55, s11, 0
	s_cmp_eq_u32 s87, 4
	s_cselect_b32 s60, s13, s54
	s_cselect_b32 s61, s12, s55
	s_cselect_b32 s58, s29, vcc_lo
	s_cselect_b32 s59, s27, vcc_hi
	s_add_u32 s56, s60, 0x200000
	s_addc_u32 s57, s61, 0
	s_add_i32 s21, 0, 0x10000
	v_add_u32_e32 v0, s21, v238
	s_add_i32 s14, 0, 0x14000
	ds_read_b128 v[58:61], v0
	ds_read_b128 v[62:65], v0 offset:1024
	ds_read_b128 v[74:77], v0 offset:2048
	ds_read_b128 v[78:81], v0 offset:3072
	v_add_u32_e32 v0, s14, v238
	ds_read_b128 v[138:141], v0
	ds_read_b128 v[142:145], v0 offset:1024
	ds_read_b128 v[146:149], v0 offset:2048
	ds_read_b128 v[150:153], v0 offset:3072
	v_lshl_add_u64 v[178:179], s[10:11], 0, v[202:203]
	s_add_i32 m0, s49, 0xc000
	ds_read_b128 v[154:157], v239
	ds_read_b128 v[166:169], v239 offset:1024
	ds_read_b128 v[170:173], v239 offset:2048
	ds_read_b128 v[174:177], v239 offset:3072
	ds_read_b128 v[206:209], v239 offset:4096
	ds_read_b128 v[210:213], v239 offset:5120
	ds_read_b128 v[214:217], v239 offset:6144
	ds_read_b128 v[218:221], v239 offset:7168
	global_load_lds_dwordx4 v[178:179], off
	v_lshl_add_u64 v[178:179], s[10:11], 0, v[204:205]
	s_add_i32 m0, s49, 0xe000
	s_nop 0
	global_load_lds_dwordx4 v[178:179], off
	s_waitcnt vmcnt(8)
	s_waitcnt lgkmcnt(0)
	s_barrier
	s_setprio 1
	s_waitcnt lgkmcnt(0)
	v_mfma_f32_16x16x32_bf16 v[162:165], v[58:61], v[154:157], 0
	v_mfma_f32_16x16x32_bf16 v[158:161], v[74:77], v[154:157], 0
	v_mfma_f32_16x16x32_bf16 v[126:129], v[58:61], v[170:173], 0
	v_mfma_f32_16x16x32_bf16 v[122:125], v[74:77], v[170:173], 0
	v_mfma_f32_16x16x32_bf16 v[110:113], v[58:61], v[206:209], 0
	v_mfma_f32_16x16x32_bf16 v[106:109], v[74:77], v[206:209], 0
	v_mfma_f32_16x16x32_bf16 v[94:97], v[58:61], v[214:217], 0
	v_mfma_f32_16x16x32_bf16 v[90:93], v[74:77], v[214:217], 0
	v_mfma_f32_16x16x32_bf16 v[162:165], v[62:65], v[166:169], v[162:165]
	v_mfma_f32_16x16x32_bf16 v[158:161], v[78:81], v[166:169], v[158:161]
	v_mfma_f32_16x16x32_bf16 v[126:129], v[62:65], v[174:177], v[126:129]
	v_mfma_f32_16x16x32_bf16 v[122:125], v[78:81], v[174:177], v[122:125]
	v_mfma_f32_16x16x32_bf16 v[110:113], v[62:65], v[210:213], v[110:113]
	v_mfma_f32_16x16x32_bf16 v[106:109], v[78:81], v[210:213], v[106:109]
	v_mfma_f32_16x16x32_bf16 v[94:97], v[62:65], v[218:221], v[94:97]
	v_mfma_f32_16x16x32_bf16 v[90:93], v[78:81], v[218:221], v[90:93]
	s_setprio 0
	s_setprio 1
	v_mfma_f32_16x16x32_bf16 v[134:137], v[138:141], v[154:157], 0
	v_mfma_f32_16x16x32_bf16 v[130:133], v[146:149], v[154:157], 0
	v_mfma_f32_16x16x32_bf16 v[118:121], v[138:141], v[170:173], 0
	v_mfma_f32_16x16x32_bf16 v[114:117], v[146:149], v[170:173], 0
	v_mfma_f32_16x16x32_bf16 v[102:105], v[138:141], v[206:209], 0
	v_mfma_f32_16x16x32_bf16 v[98:101], v[146:149], v[206:209], 0
	v_mfma_f32_16x16x32_bf16 v[86:89], v[138:141], v[214:217], 0
	v_mfma_f32_16x16x32_bf16 v[82:85], v[146:149], v[214:217], 0
	v_mfma_f32_16x16x32_bf16 v[134:137], v[142:145], v[166:169], v[134:137]
	v_mfma_f32_16x16x32_bf16 v[130:133], v[150:153], v[166:169], v[130:133]
	v_mfma_f32_16x16x32_bf16 v[118:121], v[142:145], v[174:177], v[118:121]
	v_mfma_f32_16x16x32_bf16 v[114:117], v[150:153], v[174:177], v[114:117]
	v_mfma_f32_16x16x32_bf16 v[102:105], v[142:145], v[210:213], v[102:105]
	v_mfma_f32_16x16x32_bf16 v[98:101], v[150:153], v[210:213], v[98:101]
	v_mfma_f32_16x16x32_bf16 v[86:89], v[142:145], v[218:221], v[86:89]
	v_mfma_f32_16x16x32_bf16 v[82:85], v[150:153], v[218:221], v[82:85]
	s_setprio 0
	s_barrier
	s_add_i32 s10, s21, s48
	v_lshl_add_u64 v[178:179], s[58:59], 0, v[198:199]
	s_mov_b32 m0, s10
	ds_read_b128 v[154:157], v239 offset:16384
	ds_read_b128 v[166:169], v239 offset:17408
	ds_read_b128 v[170:173], v239 offset:18432
	ds_read_b128 v[174:177], v239 offset:19456
	ds_read_b128 v[206:209], v239 offset:20480
	ds_read_b128 v[210:213], v239 offset:21504
	ds_read_b128 v[214:217], v239 offset:22528
	ds_read_b128 v[218:221], v239 offset:23552
	global_load_lds_dwordx4 v[178:179], off
	s_add_i32 m0, s10, 0x2000
	s_add_u32 s10, s58, 0x20000
	v_lshl_add_u64 v[180:181], s[58:59], 0, v[194:195]
	s_addc_u32 s11, s59, 0
	s_add_i32 s14, s14, s48
	global_load_lds_dwordx4 v[180:181], off
	v_lshl_add_u64 v[182:183], s[10:11], 0, v[198:199]
	s_mov_b32 m0, s14
	s_nop 0
	global_load_lds_dwordx4 v[182:183], off
	v_lshl_add_u64 v[182:183], s[10:11], 0, v[194:195]
	s_add_i32 m0, s14, 0x2000
	s_nop 0
	global_load_lds_dwordx4 v[182:183], off
	v_lshl_add_u64 v[182:183], s[60:61], 0, v[200:201]
	s_mov_b32 m0, s49
	s_nop 0
	global_load_lds_dwordx4 v[182:183], off
	v_lshl_add_u64 v[182:183], s[60:61], 0, v[196:197]
	s_mov_b32 m0, s76
	s_nop 0
	global_load_lds_dwordx4 v[182:183], off
	s_waitcnt vmcnt(8)
	s_waitcnt lgkmcnt(0)
	s_barrier
; #define PG8_STAGE(bufoff, gbase, voff) do { _Pragma("unroll") for (int _i = 0; _i < 2; ++_i) \
;         __builtin_amdgcn_global_load_lds((const unsigned*)((const char*)(gbase) + (voff)[_i]), (LAS unsigned*)(lds + (bufoff) + ldsw + _i * 8192), 16, 0, 0); } while (0)
; #define PG8_LDA(dst, b, h) do { _Pragma("unroll") for (int m = 0; m < 4; ++m) _Pragma("unroll") for (int k = 0; k < 2; ++k) dst[m][k] = *(const LAS bf16x8*)(lds + PG8_SA(b, h) + aoff + m * 2048 + k * 1024); } while (0)
; #define PG8_LDB(dst, b, h) do { _Pragma("unroll") for (int n = 0; n < 2; ++n) _Pragma("unroll") for (int k = 0; k < 2; ++k) dst[n][k] = *(const LAS bf16x8*)(lds + PG8_SB(b, h) + boff + n * 2048 + k * 1024); } while (0)
; #define PG8_MMA(ai, bj, At, Bt) do { __builtin_amdgcn_s_setprio(1); _Pragma("unroll") for (int m = 0; m < 4; ++m) _Pragma("unroll") for (int n = 0; n < 2; ++n) _Pragma("unroll") for (int k = 0; k < 2; ++k) \
;         acc[ai][bj][m][n] = __builtin_amdgcn_mfma_f32_16x16x32_bf16(Bt[n][k], At[m][k], acc[ai][bj][m][n], 0, 0, 0); __builtin_amdgcn_s_setprio(0); } while (0)
; #define PG8_WAIT_V(n) asm volatile("s_waitcnt vmcnt(" #n ")" ::: "memory")
; #define PG8_WAIT_L(n) asm volatile("s_waitcnt lgkmcnt(" #n ")" ::: "memory")
; #define PG8_BAR __builtin_amdgcn_s_barrier()
; #define PG8_SCHED __builtin_amdgcn_sched_barrier(0)
; template <class Epi, class Pre, bool AG = false>
; __device__ __forceinline__ void gemm_phase(LAS unsigned char* lds, const Gemm g, const StaticOrder& S, const Epi& E, const Pre& P) {
;     ...
;             PG8_WAIT_V(8); PG8_WAIT_L(0); PG8_BAR; PG8_MMA(1, 0, At, B0); PG8_MMA(1, 1, At, B1); PG8_BAR; PG8_SCHED;
;             PG8_LDB(B0, 1, 0); PG8_LDB(B1, 1, 1); PG8_SCHED; PG8_LDA(At, 1, 0); PG8_STAGE(PG8_SA(0, 1), a2 + hstepA, voffA);
;             PG8_WAIT_V(8); PG8_WAIT_L(0); PG8_BAR; PG8_MMA(0, 0, At, B0); PG8_MMA(0, 1, At, B1); PG8_BAR; PG8_SCHED;
	s_setprio 1
	s_waitcnt lgkmcnt(0)
	v_mfma_f32_16x16x32_bf16 v[70:73], v[58:61], v[154:157], 0
	v_mfma_f32_16x16x32_bf16 v[66:69], v[74:77], v[154:157], 0
	v_mfma_f32_16x16x32_bf16 v[46:49], v[58:61], v[170:173], 0
	v_mfma_f32_16x16x32_bf16 v[42:45], v[74:77], v[170:173], 0
	v_mfma_f32_16x16x32_bf16 v[30:33], v[58:61], v[206:209], 0
	v_mfma_f32_16x16x32_bf16 v[26:29], v[74:77], v[206:209], 0
	v_mfma_f32_16x16x32_bf16 v[14:17], v[58:61], v[214:217], 0
	v_mfma_f32_16x16x32_bf16 v[10:13], v[74:77], v[214:217], 0
	v_mfma_f32_16x16x32_bf16 v[70:73], v[62:65], v[166:169], v[70:73]
	v_mfma_f32_16x16x32_bf16 v[66:69], v[78:81], v[166:169], v[66:69]
	v_mfma_f32_16x16x32_bf16 v[46:49], v[62:65], v[174:177], v[46:49]
	v_mfma_f32_16x16x32_bf16 v[42:45], v[78:81], v[174:177], v[42:45]
	v_mfma_f32_16x16x32_bf16 v[30:33], v[62:65], v[210:213], v[30:33]
	v_mfma_f32_16x16x32_bf16 v[26:29], v[78:81], v[210:213], v[26:29]
	v_mfma_f32_16x16x32_bf16 v[14:17], v[62:65], v[218:221], v[14:17]
	v_mfma_f32_16x16x32_bf16 v[10:13], v[78:81], v[218:221], v[10:13]
	s_setprio 0
	s_setprio 1
	v_mfma_f32_16x16x32_bf16 v[54:57], v[138:141], v[154:157], 0
	v_mfma_f32_16x16x32_bf16 v[50:53], v[146:149], v[154:157], 0
	v_mfma_f32_16x16x32_bf16 v[38:41], v[138:141], v[170:173], 0
	v_mfma_f32_16x16x32_bf16 v[34:37], v[146:149], v[170:173], 0
	v_mfma_f32_16x16x32_bf16 v[22:25], v[138:141], v[206:209], 0
	v_mfma_f32_16x16x32_bf16 v[18:21], v[146:149], v[206:209], 0
	v_mfma_f32_16x16x32_bf16 v[6:9], v[138:141], v[214:217], 0
	v_mfma_f32_16x16x32_bf16 v[2:5], v[146:149], v[214:217], 0
	v_mfma_f32_16x16x32_bf16 v[54:57], v[142:145], v[166:169], v[54:57]
	v_mfma_f32_16x16x32_bf16 v[50:53], v[150:153], v[166:169], v[50:53]
	v_mfma_f32_16x16x32_bf16 v[38:41], v[142:145], v[174:177], v[38:41]
	v_mfma_f32_16x16x32_bf16 v[34:37], v[150:153], v[174:177], v[34:37]
	v_mfma_f32_16x16x32_bf16 v[22:25], v[142:145], v[210:213], v[22:25]
	v_mfma_f32_16x16x32_bf16 v[18:21], v[150:153], v[210:213], v[18:21]
	v_mfma_f32_16x16x32_bf16 v[6:9], v[142:145], v[218:221], v[6:9]
	v_mfma_f32_16x16x32_bf16 v[2:5], v[150:153], v[218:221], v[2:5]
	s_setprio 0
	s_barrier
	s_add_i32 s14, 0, 0x18000
	v_add_u32_e32 v0, s14, v238
	s_add_i32 s21, 0, 0x1c000
	ds_read_b128 v[58:61], v0
	ds_read_b128 v[62:65], v0 offset:1024
	ds_read_b128 v[74:77], v0 offset:2048
	ds_read_b128 v[78:81], v0 offset:3072
	v_add_u32_e32 v0, s21, v238
	ds_read_b128 v[138:141], v0
	ds_read_b128 v[142:145], v0 offset:1024
	ds_read_b128 v[146:149], v0 offset:2048
	ds_read_b128 v[150:153], v0 offset:3072
	s_add_u32 s10, s60, 0x1000
	s_addc_u32 s11, s61, 0
	s_mov_b32 m0, s77
	v_lshl_add_u64 v[182:183], s[10:11], 0, v[200:201]
	ds_read_b128 v[154:157], v239 offset:32768
	ds_read_b128 v[166:169], v239 offset:33792
	ds_read_b128 v[170:173], v239 offset:34816
	ds_read_b128 v[174:177], v239 offset:35840
	ds_read_b128 v[206:209], v239 offset:36864
	ds_read_b128 v[210:213], v239 offset:37888
	ds_read_b128 v[214:217], v239 offset:38912
	ds_read_b128 v[218:221], v239 offset:39936
	global_load_lds_dwordx4 v[182:183], off
	v_lshl_add_u64 v[182:183], s[10:11], 0, v[196:197]
	s_mov_b32 m0, s84
	s_nop 0
	global_load_lds_dwordx4 v[182:183], off
	s_waitcnt vmcnt(8)
	s_waitcnt lgkmcnt(0)
	s_barrier
	s_setprio 1
	s_waitcnt lgkmcnt(0)
	v_mfma_f32_16x16x32_bf16 v[162:165], v[58:61], v[154:157], v[162:165]
	v_mfma_f32_16x16x32_bf16 v[158:161], v[74:77], v[154:157], v[158:161]
	v_mfma_f32_16x16x32_bf16 v[126:129], v[58:61], v[170:173], v[126:129]
	v_mfma_f32_16x16x32_bf16 v[122:125], v[74:77], v[170:173], v[122:125]
	v_mfma_f32_16x16x32_bf16 v[110:113], v[58:61], v[206:209], v[110:113]
	v_mfma_f32_16x16x32_bf16 v[106:109], v[74:77], v[206:209], v[106:109]
	v_mfma_f32_16x16x32_bf16 v[94:97], v[58:61], v[214:217], v[94:97]
	v_mfma_f32_16x16x32_bf16 v[90:93], v[74:77], v[214:217], v[90:93]
	v_mfma_f32_16x16x32_bf16 v[162:165], v[62:65], v[166:169], v[162:165]
	v_mfma_f32_16x16x32_bf16 v[158:161], v[78:81], v[166:169], v[158:161]
	v_mfma_f32_16x16x32_bf16 v[126:129], v[62:65], v[174:177], v[126:129]
	v_mfma_f32_16x16x32_bf16 v[122:125], v[78:81], v[174:177], v[122:125]
	v_mfma_f32_16x16x32_bf16 v[110:113], v[62:65], v[210:213], v[110:113]
	v_mfma_f32_16x16x32_bf16 v[106:109], v[78:81], v[210:213], v[106:109]
	v_mfma_f32_16x16x32_bf16 v[94:97], v[62:65], v[218:221], v[94:97]
	v_mfma_f32_16x16x32_bf16 v[90:93], v[78:81], v[218:221], v[90:93]
	s_setprio 0
	s_setprio 1
	v_mfma_f32_16x16x32_bf16 v[134:137], v[138:141], v[154:157], v[134:137]
	v_mfma_f32_16x16x32_bf16 v[130:133], v[146:149], v[154:157], v[130:133]
	v_mfma_f32_16x16x32_bf16 v[118:121], v[138:141], v[170:173], v[118:121]
	v_mfma_f32_16x16x32_bf16 v[114:117], v[146:149], v[170:173], v[114:117]
	v_mfma_f32_16x16x32_bf16 v[102:105], v[138:141], v[206:209], v[102:105]
	v_mfma_f32_16x16x32_bf16 v[98:101], v[146:149], v[206:209], v[98:101]
	v_mfma_f32_16x16x32_bf16 v[86:89], v[138:141], v[214:217], v[86:89]
	v_mfma_f32_16x16x32_bf16 v[82:85], v[146:149], v[214:217], v[82:85]
	v_mfma_f32_16x16x32_bf16 v[134:137], v[142:145], v[166:169], v[134:137]
	v_mfma_f32_16x16x32_bf16 v[130:133], v[150:153], v[166:169], v[130:133]
	v_mfma_f32_16x16x32_bf16 v[118:121], v[142:145], v[174:177], v[118:121]
	v_mfma_f32_16x16x32_bf16 v[114:117], v[150:153], v[174:177], v[114:117]
	v_mfma_f32_16x16x32_bf16 v[102:105], v[142:145], v[210:213], v[102:105]
	v_mfma_f32_16x16x32_bf16 v[98:101], v[150:153], v[210:213], v[98:101]
	v_mfma_f32_16x16x32_bf16 v[86:89], v[142:145], v[218:221], v[86:89]
	v_mfma_f32_16x16x32_bf16 v[82:85], v[150:153], v[218:221], v[82:85]
	s_setprio 0
	s_barrier
; #define PG8_STAGE(bufoff, gbase, voff) do { _Pragma("unroll") for (int _i = 0; _i < 2; ++_i) \
;         __builtin_amdgcn_global_load_lds((const unsigned*)((const char*)(gbase) + (voff)[_i]), (LAS unsigned*)(lds + (bufoff) + ldsw + _i * 8192), 16, 0, 0); } while (0)
; #define PG8_LDA(dst, b, h) do { _Pragma("unroll") for (int m = 0; m < 4; ++m) _Pragma("unroll") for (int k = 0; k < 2; ++k) dst[m][k] = *(const LAS bf16x8*)(lds + PG8_SA(b, h) + aoff + m * 2048 + k * 1024); } while (0)
; #define PG8_MMA(ai, bj, At, Bt) do { __builtin_amdgcn_s_setprio(1); _Pragma("unroll") for (int m = 0; m < 4; ++m) _Pragma("unroll") for (int n = 0; n < 2; ++n) _Pragma("unroll") for (int k = 0; k < 2; ++k) \
;         acc[ai][bj][m][n] = __builtin_amdgcn_mfma_f32_16x16x32_bf16(Bt[n][k], At[m][k], acc[ai][bj][m][n], 0, 0, 0); __builtin_amdgcn_s_setprio(0); } while (0)
; #define PG8_WAIT_V(n) asm volatile("s_waitcnt vmcnt(" #n ")" ::: "memory")
; #define PG8_WAIT_L(n) asm volatile("s_waitcnt lgkmcnt(" #n ")" ::: "memory")
; #define PG8_BAR __builtin_amdgcn_s_barrier()
; #define PG8_SCHED __builtin_amdgcn_sched_barrier(0)
; template <class Epi, class Pre, bool AG = false>
; __device__ __forceinline__ void gemm_phase(LAS unsigned char* lds, const Gemm g, const StaticOrder& S, const Epi& E, const Pre& P) {
;     ...
;         for (int t = 0; t < nt; t += 2) {
;     ...
;             PG8_LDA(At, 1, 1); PG8_STAGE(PG8_SB(1, 0), b3, voffB); PG8_STAGE(PG8_SB(1, 1), b3 + hstep, voffB); PG8_STAGE(PG8_SA(1, 0), a3, voffA);
;             PG8_WAIT_V(8); PG8_WAIT_L(0); PG8_BAR; PG8_MMA(1, 0, At, B0); PG8_MMA(1, 1, At, B1); PG8_BAR; PG8_SCHED;
	s_add_i32 s10, s14, s48
	v_lshl_add_u64 v[178:179], v[178:179], 0, s[66:67]
	s_mov_b32 m0, s10
	ds_read_b128 v[154:157], v239 offset:49152
	ds_read_b128 v[166:169], v239 offset:50176
	ds_read_b128 v[170:173], v239 offset:51200
	ds_read_b128 v[174:177], v239 offset:52224
	ds_read_b128 v[206:209], v239 offset:53248
	ds_read_b128 v[210:213], v239 offset:54272
	ds_read_b128 v[214:217], v239 offset:55296
	ds_read_b128 v[218:221], v239 offset:56320
	global_load_lds_dwordx4 v[178:179], off
	s_add_i32 m0, s10, 0x2000
	s_add_u32 s10, s58, 0x20080
	v_lshl_add_u64 v[178:179], v[180:181], 0, s[66:67]
	s_addc_u32 s11, s59, 0
	s_add_i32 s14, s21, s48
	global_load_lds_dwordx4 v[178:179], off
	v_lshl_add_u64 v[178:179], s[10:11], 0, v[198:199]
	s_mov_b32 m0, s14
	s_nop 0
	global_load_lds_dwordx4 v[178:179], off
	v_lshl_add_u64 v[178:179], s[10:11], 0, v[194:195]
	s_add_i32 m0, s14, 0x2000
	s_nop 0
	global_load_lds_dwordx4 v[178:179], off
	v_lshl_add_u64 v[178:179], s[56:57], 0, v[200:201]
	s_mov_b32 m0, s24
	s_nop 0
	global_load_lds_dwordx4 v[178:179], off
	v_lshl_add_u64 v[178:179], s[56:57], 0, v[196:197]
	s_mov_b32 m0, s25
	s_nop 0
	global_load_lds_dwordx4 v[178:179], off
	s_waitcnt vmcnt(8)
	s_waitcnt lgkmcnt(0)
	s_barrier
	s_setprio 1
	s_waitcnt lgkmcnt(0)
	v_mfma_f32_16x16x32_bf16 v[70:73], v[58:61], v[154:157], v[70:73]
	v_mfma_f32_16x16x32_bf16 v[66:69], v[74:77], v[154:157], v[66:69]
	v_mfma_f32_16x16x32_bf16 v[46:49], v[58:61], v[170:173], v[46:49]
	v_mfma_f32_16x16x32_bf16 v[42:45], v[74:77], v[170:173], v[42:45]
	v_mfma_f32_16x16x32_bf16 v[30:33], v[58:61], v[206:209], v[30:33]
	v_mfma_f32_16x16x32_bf16 v[26:29], v[74:77], v[206:209], v[26:29]
	v_mfma_f32_16x16x32_bf16 v[14:17], v[58:61], v[214:217], v[14:17]
	v_mfma_f32_16x16x32_bf16 v[10:13], v[74:77], v[214:217], v[10:13]
	v_mfma_f32_16x16x32_bf16 v[70:73], v[62:65], v[166:169], v[70:73]
	v_mfma_f32_16x16x32_bf16 v[66:69], v[78:81], v[166:169], v[66:69]
	v_mfma_f32_16x16x32_bf16 v[46:49], v[62:65], v[174:177], v[46:49]
	v_mfma_f32_16x16x32_bf16 v[42:45], v[78:81], v[174:177], v[42:45]
	v_mfma_f32_16x16x32_bf16 v[30:33], v[62:65], v[210:213], v[30:33]
	v_mfma_f32_16x16x32_bf16 v[26:29], v[78:81], v[210:213], v[26:29]
	v_mfma_f32_16x16x32_bf16 v[14:17], v[62:65], v[218:221], v[14:17]
	v_mfma_f32_16x16x32_bf16 v[10:13], v[78:81], v[218:221], v[10:13]
	s_setprio 0
	s_setprio 1
	v_mfma_f32_16x16x32_bf16 v[54:57], v[138:141], v[154:157], v[54:57]
	v_mfma_f32_16x16x32_bf16 v[50:53], v[146:149], v[154:157], v[50:53]
	v_mfma_f32_16x16x32_bf16 v[38:41], v[138:141], v[170:173], v[38:41]
	v_mfma_f32_16x16x32_bf16 v[34:37], v[146:149], v[170:173], v[34:37]
	v_mfma_f32_16x16x32_bf16 v[22:25], v[138:141], v[206:209], v[22:25]
	v_mfma_f32_16x16x32_bf16 v[18:21], v[146:149], v[206:209], v[18:21]
	v_mfma_f32_16x16x32_bf16 v[6:9], v[138:141], v[214:217], v[6:9]
	v_mfma_f32_16x16x32_bf16 v[2:5], v[146:149], v[214:217], v[2:5]
	v_mfma_f32_16x16x32_bf16 v[54:57], v[142:145], v[166:169], v[54:57]
	v_mfma_f32_16x16x32_bf16 v[50:53], v[150:153], v[166:169], v[50:53]
	v_mfma_f32_16x16x32_bf16 v[38:41], v[142:145], v[174:177], v[38:41]
	v_mfma_f32_16x16x32_bf16 v[34:37], v[150:153], v[174:177], v[34:37]
	v_mfma_f32_16x16x32_bf16 v[22:25], v[142:145], v[210:213], v[22:25]
	v_mfma_f32_16x16x32_bf16 v[18:21], v[150:153], v[210:213], v[18:21]
	v_mfma_f32_16x16x32_bf16 v[6:9], v[142:145], v[218:221], v[6:9]
	v_mfma_f32_16x16x32_bf16 v[2:5], v[150:153], v[218:221], v[2:5]
	s_setprio 0
	s_barrier
	s_add_i32 s87, s87, 2
	s_add_u32 vcc_lo, vcc_lo, 0x100
	s_addc_u32 vcc_hi, vcc_hi, 0
	s_cmp_gt_u32 s87, 5
	s_mov_b64 s[10:11], s[54:55]
	s_cbranch_scc0 .LBB0_741
	s_branch .Lpeel_glu_after

; #define PG8_BAR __builtin_amdgcn_s_barrier()
; template <class Epi, class Pre, bool AG = false>
; __device__ __forceinline__ void gemm_phase(LAS unsigned char* lds, const Gemm g, const StaticOrder& S, const Epi& E, const Pre& P) {
;     ...
;         if (wr == 0) PG8_BAR;
.Lpeel_glu_after:
	s_and_b64 vcc, exec, s[94:95]
	s_cbranch_vccz .LBB0_744
	s_barrier
